# P8+P9 fused: sub-key scores computed from the LDS-staged bf16 query tile in the P8 epilogue (bf16 MFMA, f16 store, same layout), Qp round trip and phase-9 loop removed; score rows of hc<8 relocated to
# speedup vs baseline: 1.0089x; 1.0036x over previous
; DI unsigned pack2bf(float a, float b) { const f2_t v = {a, b}; return __builtin_bit_cast(unsigned, __builtin_convertvector(v, bf2_t)); }
; template <class Epi>
; DI void gemm_tile256(const u16* __restrict__ Ag, long lda, const u16* __restrict__ Bg, long ldb, int nk, char* shm, Epi&& epi) {
;     ...
;   __syncthreads();
; #pragma unroll
;   for (int m = 0; m < 8; ++m)
; #pragma unroll
;     for (int n = 0; n < 4; ++n) epi(wr * 128 + m * 16 + fr, wc * 64 + n * 16 + fq * 4, acc[m][n]);
; DI void phase8(const Params& P, char* smem) {
;     ...
;     gemm_tile256(h1b + (long)brow * 1024, 1024, WqT + (long)bcol * 1024, 1024, 32, smem, [&](int row, int col0, f32x4 v) {
;       *reinterpret_cast<uint2*>(Qp + (long)(brow + row) * 2048 + bcol + col0) = make_uint2(pack2bf(v[0], v[1]), pack2bf(v[2], v[3]));
;     });
.Lgemm_p8_kend:
	s_nop 7
	s_nop 3
	s_waitcnt vmcnt(0) lgkmcnt(0)
	s_barrier
	v_and_b32_e32 v186, 15, v208
	v_lshrrev_b32_e32 v187, 4, v208
	v_lshrrev_b32_e32 v206, 6, v189
	v_lshlrev_b32_e32 v206, 14, v206
	v_and_b32_e32 v207, 7, v186
	v_lshrrev_b32_e32 v224, 1, v187
	v_and_b32_e32 v225, 1, v187
	v_lshl_add_u32 v226, v186, 7, v206
	v_lshl_add_u32 v226, v225, 3, v226
	v_or_b32_e32 v227, 0, v224
	v_xor_b32_e32 v227, v227, v207
	v_lshl_add_u32 v232, v227, 4, v226
	v_or_b32_e32 v227, 2, v224
	v_xor_b32_e32 v227, v227, v207
	v_lshl_add_u32 v233, v227, 4, v226
	v_or_b32_e32 v227, 4, v224
	v_xor_b32_e32 v227, v227, v207
	v_lshl_add_u32 v234, v227, 4, v226
	v_or_b32_e32 v227, 6, v224
	v_xor_b32_e32 v227, v227, v207
	v_lshl_add_u32 v235, v227, 4, v226
	v_lshrrev_b32_e32 v228, 3, v208
	v_and_b32_e32 v229, 7, v208
	v_xor_b32_e32 v227, v229, v228
	v_lshl_add_u32 v236, v228, 7, v206
	v_lshl_add_u32 v236, v227, 4, v236
	v_lshl_add_u32 v227, v190, 7, v228
	v_add_u32_e32 v227, s10, v227
	v_lshlrev_b32_e32 v238, 12, v227
	v_bfe_u32 v227, v189, 6, 2
	v_lshl_add_u32 v238, v227, 7, v238
	v_lshl_add_u32 v238, v229, 4, v238
	v_mov_b32_e32 v239, 0
	s_and_b32 s26, s74, 7
	s_lshl_b32 s26, s26, 9
	s_add_u32 s26, s26, 0x8000000
	s_add_u32 s26, s78, s26
	s_addc_u32 s27, s79, 0
	v_lshl_add_u64 v[238:239], v[238:239], 0, s[26:27]
	s_mov_b32 s28, 0x8000
	s_mov_b32 s29, 0
	v_lshl_add_u64 v[240:241], v[238:239], 0, s[28:29]
	s_lshl_b32 s28, s28, 1
	v_cvt_pk_bf16_f32 v124, v124, v125
	v_cvt_pk_bf16_f32 v125, v126, v127
	ds_write_b64 v232, v[124:125] offset:0
	v_cvt_pk_bf16_f32 v120, v120, v121
	v_cvt_pk_bf16_f32 v121, v122, v123
	ds_write_b64 v233, v[120:121] offset:0
	v_cvt_pk_bf16_f32 v116, v116, v117
	v_cvt_pk_bf16_f32 v117, v118, v119
	ds_write_b64 v234, v[116:117] offset:0
	v_cvt_pk_bf16_f32 v112, v112, v113
	v_cvt_pk_bf16_f32 v113, v114, v115
	ds_write_b64 v235, v[112:113] offset:0
	v_cvt_pk_bf16_f32 v108, v108, v109
	v_cvt_pk_bf16_f32 v109, v110, v111
	ds_write_b64 v232, v[108:109] offset:2048
	v_cvt_pk_bf16_f32 v104, v104, v105
	v_cvt_pk_bf16_f32 v105, v106, v107
	ds_write_b64 v233, v[104:105] offset:2048
	v_cvt_pk_bf16_f32 v100, v100, v101
	v_cvt_pk_bf16_f32 v101, v102, v103
	ds_write_b64 v234, v[100:101] offset:2048
	v_cvt_pk_bf16_f32 v96, v96, v97
	v_cvt_pk_bf16_f32 v97, v98, v99
	ds_write_b64 v235, v[96:97] offset:2048
	v_cvt_pk_bf16_f32 v92, v92, v93
	v_cvt_pk_bf16_f32 v93, v94, v95
	ds_write_b64 v232, v[92:93] offset:4096
	v_cvt_pk_bf16_f32 v88, v88, v89
	v_cvt_pk_bf16_f32 v89, v90, v91
	ds_write_b64 v233, v[88:89] offset:4096
	v_cvt_pk_bf16_f32 v84, v84, v85
	v_cvt_pk_bf16_f32 v85, v86, v87
	ds_write_b64 v234, v[84:85] offset:4096
	v_cvt_pk_bf16_f32 v80, v80, v81
	v_cvt_pk_bf16_f32 v81, v82, v83
	ds_write_b64 v235, v[80:81] offset:4096
	v_cvt_pk_bf16_f32 v76, v76, v77
	v_cvt_pk_bf16_f32 v77, v78, v79
	ds_write_b64 v232, v[76:77] offset:6144
	v_cvt_pk_bf16_f32 v72, v72, v73
	v_cvt_pk_bf16_f32 v73, v74, v75
	ds_write_b64 v233, v[72:73] offset:6144
	v_cvt_pk_bf16_f32 v68, v68, v69
	v_cvt_pk_bf16_f32 v69, v70, v71
	ds_write_b64 v234, v[68:69] offset:6144
	v_cvt_pk_bf16_f32 v64, v64, v65
	v_cvt_pk_bf16_f32 v65, v66, v67
	ds_write_b64 v235, v[64:65] offset:6144
	v_cvt_pk_bf16_f32 v60, v60, v61
	v_cvt_pk_bf16_f32 v61, v62, v63
	ds_write_b64 v232, v[60:61] offset:8192
	v_cvt_pk_bf16_f32 v56, v56, v57
	v_cvt_pk_bf16_f32 v57, v58, v59
	ds_write_b64 v233, v[56:57] offset:8192
	v_cvt_pk_bf16_f32 v52, v52, v53
	v_cvt_pk_bf16_f32 v53, v54, v55
	ds_write_b64 v234, v[52:53] offset:8192
	v_cvt_pk_bf16_f32 v48, v48, v49
	v_cvt_pk_bf16_f32 v49, v50, v51
	ds_write_b64 v235, v[48:49] offset:8192
	v_cvt_pk_bf16_f32 v44, v44, v45
	v_cvt_pk_bf16_f32 v45, v46, v47
	ds_write_b64 v232, v[44:45] offset:10240
	v_cvt_pk_bf16_f32 v40, v40, v41
	v_cvt_pk_bf16_f32 v41, v42, v43
	ds_write_b64 v233, v[40:41] offset:10240
	v_cvt_pk_bf16_f32 v36, v36, v37
	v_cvt_pk_bf16_f32 v37, v38, v39
	ds_write_b64 v234, v[36:37] offset:10240
	v_cvt_pk_bf16_f32 v32, v32, v33
	v_cvt_pk_bf16_f32 v33, v34, v35
	ds_write_b64 v235, v[32:33] offset:10240
	v_cvt_pk_bf16_f32 v28, v28, v29
	v_cvt_pk_bf16_f32 v29, v30, v31
	ds_write_b64 v232, v[28:29] offset:12288
	v_cvt_pk_bf16_f32 v24, v24, v25
	v_cvt_pk_bf16_f32 v25, v26, v27
	ds_write_b64 v233, v[24:25] offset:12288
	v_cvt_pk_bf16_f32 v20, v20, v21
	v_cvt_pk_bf16_f32 v21, v22, v23
	ds_write_b64 v234, v[20:21] offset:12288
	v_cvt_pk_bf16_f32 v16, v16, v17
	v_cvt_pk_bf16_f32 v17, v18, v19
	ds_write_b64 v235, v[16:17] offset:12288
	v_cvt_pk_bf16_f32 v12, v12, v13
	v_cvt_pk_bf16_f32 v13, v14, v15
	ds_write_b64 v232, v[12:13] offset:14336
	v_cvt_pk_bf16_f32 v8, v8, v9
	v_cvt_pk_bf16_f32 v9, v10, v11
	ds_write_b64 v233, v[8:9] offset:14336
	v_cvt_pk_bf16_f32 v4, v4, v5
	v_cvt_pk_bf16_f32 v5, v6, v7
	ds_write_b64 v234, v[4:5] offset:14336
	v_cvt_pk_bf16_f32 v0, v0, v1
	v_cvt_pk_bf16_f32 v1, v2, v3
	ds_write_b64 v235, v[0:1] offset:14336
	s_waitcnt lgkmcnt(0)
	s_barrier
; DI void phase9(const Params& P, char* smem) {
;     ...
;     const int brow = (tile >> 4) * 128, hc = tile & 15;
;     gemm_tile<false>(Qp + (long)brow * 2048 + hc * 128, 2048, SKb + (long)hc * 128 * 128, 128, 0, 2, 0, 0, smem, [&](int row0, int col, f32x4 v) {
;       typedef _Float16 h4 __attribute__((ext_vector_type(4)));
;       h4 hv; hv[0] = (_Float16)v[0]; hv[1] = (_Float16)v[1]; hv[2] = (_Float16)v[2]; hv[3] = (_Float16)v[3];
;       *reinterpret_cast<h4*>(ST + ((long)(hc * 128 + col)) * NTOK + brow + row0) = hv;
;     });
	v_lshrrev_b32_e32 v224, 6, v189
	v_lshrrev_b32_e32 v225, 2, v224
	v_and_b32_e32 v226, 3, v224
	v_lshlrev_b32_e32 v225, 16, v225
	v_lshl_add_u32 v226, v226, 5, v186
	v_lshl_add_u32 v225, v226, 7, v225
	v_and_b32_e32 v227, 7, v186
	v_xor_b32_e32 v227, v227, v187
	v_lshl_add_u32 v232, v227, 4, v225
	v_xor_b32_e32 v227, 4, v227
	v_lshl_add_u32 v233, v227, 4, v225
	ds_read_b128 v[0:3], v232 offset:0
	ds_read_b128 v[4:7], v233 offset:0
	ds_read_b128 v[8:11], v232 offset:16384
	ds_read_b128 v[12:15], v233 offset:16384
	ds_read_b128 v[16:19], v232 offset:32768
	ds_read_b128 v[20:23], v233 offset:32768
	ds_read_b128 v[24:27], v232 offset:49152
	ds_read_b128 v[28:31], v233 offset:49152
	ds_read_b128 v[32:35], v232 offset:2048
	ds_read_b128 v[36:39], v233 offset:2048
	ds_read_b128 v[40:43], v232 offset:18432
	ds_read_b128 v[44:47], v233 offset:18432
	ds_read_b128 v[48:51], v232 offset:34816
	ds_read_b128 v[52:55], v233 offset:34816
	ds_read_b128 v[56:59], v232 offset:51200
	ds_read_b128 v[60:63], v233 offset:51200
	s_and_b32 s26, s74, 7
	s_lshl_b32 s26, s26, 16
	s_add_u32 s26, s26, 0x18a80000
	s_add_u32 s26, s78, s26
	s_addc_u32 s27, s79, 0
	v_lshlrev_b32_e32 v234, 8, v186
	v_lshl_add_u32 v234, v187, 4, v234
	s_and_b32 s28, s74, 7
	s_cmp_lt_u32 s28, 4
	s_cselect_b32 s29, 0x6000000, 0
	s_sub_u32 s29, 0x10000000, s29
	s_lshl_b32 s28, s28, 24
	s_add_u32 s28, s28, s29
	s_add_u32 s28, s78, s28
	s_addc_u32 s29, s79, 0
	v_lshl_add_u32 v236, v224, 5, s10
	v_lshl_add_u32 v236, v187, 2, v236
	v_lshlrev_b32_e32 v236, 1, v236
	v_lshl_add_u32 v236, v186, 16, v236
	v_add_u32_e32 v235, 0x0, v234
	global_load_dwordx4 v[64:67], v235, s[26:27] offset:0
	global_load_dwordx4 v[68:71], v235, s[26:27] offset:64
	global_load_dwordx4 v[72:75], v235, s[26:27] offset:128
	global_load_dwordx4 v[76:79], v235, s[26:27] offset:192
	v_add_u32_e32 v235, 0x1000, v234
	global_load_dwordx4 v[80:83], v235, s[26:27] offset:0
	global_load_dwordx4 v[84:87], v235, s[26:27] offset:64
	global_load_dwordx4 v[88:91], v235, s[26:27] offset:128
	global_load_dwordx4 v[92:95], v235, s[26:27] offset:192
	s_waitcnt vmcnt(4) lgkmcnt(0)
	v_mfma_f32_16x16x32_bf16 v[96:99], v[0:3], v[64:67], 0
	v_mfma_f32_16x16x32_bf16 v[96:99], v[4:7], v[68:71], v[96:99]
	v_mfma_f32_16x16x32_bf16 v[96:99], v[8:11], v[72:75], v[96:99]
	v_mfma_f32_16x16x32_bf16 v[96:99], v[12:15], v[76:79], v[96:99]
	v_mfma_f32_16x16x32_bf16 v[100:103], v[32:35], v[64:67], 0
	v_mfma_f32_16x16x32_bf16 v[100:103], v[36:39], v[68:71], v[100:103]
	v_mfma_f32_16x16x32_bf16 v[100:103], v[40:43], v[72:75], v[100:103]
	v_mfma_f32_16x16x32_bf16 v[100:103], v[44:47], v[76:79], v[100:103]
	s_nop 7
	s_nop 3
	v_cvt_pk_f16_f32 v104, v96, v97
	v_cvt_pk_f16_f32 v105, v98, v99
	v_cvt_pk_f16_f32 v106, v100, v101
	v_cvt_pk_f16_f32 v107, v102, v103
	v_add_u32_e32 v238, 0x0, v236
	global_store_dwordx2 v238, v[104:105], s[28:29]
	global_store_dwordx2 v238, v[106:107], s[28:29] offset:32
	v_add_u32_e32 v235, 0x2000, v234
	global_load_dwordx4 v[64:67], v235, s[26:27] offset:0
	global_load_dwordx4 v[68:71], v235, s[26:27] offset:64
	global_load_dwordx4 v[72:75], v235, s[26:27] offset:128
	global_load_dwordx4 v[76:79], v235, s[26:27] offset:192
	s_waitcnt vmcnt(6)
	v_mfma_f32_16x16x32_bf16 v[96:99], v[0:3], v[80:83], 0
	v_mfma_f32_16x16x32_bf16 v[96:99], v[4:7], v[84:87], v[96:99]
	v_mfma_f32_16x16x32_bf16 v[96:99], v[8:11], v[88:91], v[96:99]
	v_mfma_f32_16x16x32_bf16 v[96:99], v[12:15], v[92:95], v[96:99]
	v_mfma_f32_16x16x32_bf16 v[100:103], v[32:35], v[80:83], 0
	v_mfma_f32_16x16x32_bf16 v[100:103], v[36:39], v[84:87], v[100:103]
	v_mfma_f32_16x16x32_bf16 v[100:103], v[40:43], v[88:91], v[100:103]
	v_mfma_f32_16x16x32_bf16 v[100:103], v[44:47], v[92:95], v[100:103]
	s_nop 7
	s_nop 3
	v_cvt_pk_f16_f32 v104, v96, v97
	v_cvt_pk_f16_f32 v105, v98, v99
	v_cvt_pk_f16_f32 v106, v100, v101
	v_cvt_pk_f16_f32 v107, v102, v103
	v_add_u32_e32 v238, 0x100000, v236
	global_store_dwordx2 v238, v[104:105], s[28:29]
	global_store_dwordx2 v238, v[106:107], s[28:29] offset:32
	v_add_u32_e32 v235, 0x3000, v234
	global_load_dwordx4 v[80:83], v235, s[26:27] offset:0
	global_load_dwordx4 v[84:87], v235, s[26:27] offset:64
	global_load_dwordx4 v[88:91], v235, s[26:27] offset:128
	global_load_dwordx4 v[92:95], v235, s[26:27] offset:192
	s_waitcnt vmcnt(6)
	v_mfma_f32_16x16x32_bf16 v[96:99], v[0:3], v[64:67], 0
	v_mfma_f32_16x16x32_bf16 v[96:99], v[4:7], v[68:71], v[96:99]
	v_mfma_f32_16x16x32_bf16 v[96:99], v[8:11], v[72:75], v[96:99]
	v_mfma_f32_16x16x32_bf16 v[96:99], v[12:15], v[76:79], v[96:99]
	v_mfma_f32_16x16x32_bf16 v[100:103], v[32:35], v[64:67], 0
	v_mfma_f32_16x16x32_bf16 v[100:103], v[36:39], v[68:71], v[100:103]
	v_mfma_f32_16x16x32_bf16 v[100:103], v[40:43], v[72:75], v[100:103]
	v_mfma_f32_16x16x32_bf16 v[100:103], v[44:47], v[76:79], v[100:103]
	s_nop 7
	s_nop 3
	v_cvt_pk_f16_f32 v104, v96, v97
	v_cvt_pk_f16_f32 v105, v98, v99
	v_cvt_pk_f16_f32 v106, v100, v101
	v_cvt_pk_f16_f32 v107, v102, v103
	v_add_u32_e32 v238, 0x200000, v236
	global_store_dwordx2 v238, v[104:105], s[28:29]
	global_store_dwordx2 v238, v[106:107], s[28:29] offset:32
	v_add_u32_e32 v235, 0x4000, v234
	global_load_dwordx4 v[64:67], v235, s[26:27] offset:0
	global_load_dwordx4 v[68:71], v235, s[26:27] offset:64
	global_load_dwordx4 v[72:75], v235, s[26:27] offset:128
	global_load_dwordx4 v[76:79], v235, s[26:27] offset:192
	s_waitcnt vmcnt(6)
; DI void phase9(const Params& P, char* smem) {
;     ...
;     const int brow = (tile >> 4) * 128, hc = tile & 15;
;     gemm_tile<false>(Qp + (long)brow * 2048 + hc * 128, 2048, SKb + (long)hc * 128 * 128, 128, 0, 2, 0, 0, smem, [&](int row0, int col, f32x4 v) {
;       typedef _Float16 h4 __attribute__((ext_vector_type(4)));
;       h4 hv; hv[0] = (_Float16)v[0]; hv[1] = (_Float16)v[1]; hv[2] = (_Float16)v[2]; hv[3] = (_Float16)v[3];
;       *reinterpret_cast<h4*>(ST + ((long)(hc * 128 + col)) * NTOK + brow + row0) = hv;
;     });
	v_mfma_f32_16x16x32_bf16 v[96:99], v[0:3], v[80:83], 0
	v_mfma_f32_16x16x32_bf16 v[96:99], v[4:7], v[84:87], v[96:99]
	v_mfma_f32_16x16x32_bf16 v[96:99], v[8:11], v[88:91], v[96:99]
	v_mfma_f32_16x16x32_bf16 v[96:99], v[12:15], v[92:95], v[96:99]
	v_mfma_f32_16x16x32_bf16 v[100:103], v[32:35], v[80:83], 0
	v_mfma_f32_16x16x32_bf16 v[100:103], v[36:39], v[84:87], v[100:103]
	v_mfma_f32_16x16x32_bf16 v[100:103], v[40:43], v[88:91], v[100:103]
	v_mfma_f32_16x16x32_bf16 v[100:103], v[44:47], v[92:95], v[100:103]
	s_nop 7
	s_nop 3
	v_cvt_pk_f16_f32 v104, v96, v97
	v_cvt_pk_f16_f32 v105, v98, v99
	v_cvt_pk_f16_f32 v106, v100, v101
	v_cvt_pk_f16_f32 v107, v102, v103
	v_add_u32_e32 v238, 0x300000, v236
	global_store_dwordx2 v238, v[104:105], s[28:29]
	global_store_dwordx2 v238, v[106:107], s[28:29] offset:32
	v_add_u32_e32 v235, 0x5000, v234
	global_load_dwordx4 v[80:83], v235, s[26:27] offset:0
	global_load_dwordx4 v[84:87], v235, s[26:27] offset:64
	global_load_dwordx4 v[88:91], v235, s[26:27] offset:128
	global_load_dwordx4 v[92:95], v235, s[26:27] offset:192
	s_waitcnt vmcnt(6)
	v_mfma_f32_16x16x32_bf16 v[96:99], v[0:3], v[64:67], 0
	v_mfma_f32_16x16x32_bf16 v[96:99], v[4:7], v[68:71], v[96:99]
	v_mfma_f32_16x16x32_bf16 v[96:99], v[8:11], v[72:75], v[96:99]
	v_mfma_f32_16x16x32_bf16 v[96:99], v[12:15], v[76:79], v[96:99]
	v_mfma_f32_16x16x32_bf16 v[100:103], v[32:35], v[64:67], 0
	v_mfma_f32_16x16x32_bf16 v[100:103], v[36:39], v[68:71], v[100:103]
	v_mfma_f32_16x16x32_bf16 v[100:103], v[40:43], v[72:75], v[100:103]
	v_mfma_f32_16x16x32_bf16 v[100:103], v[44:47], v[76:79], v[100:103]
	s_nop 7
	s_nop 3
	v_cvt_pk_f16_f32 v104, v96, v97
	v_cvt_pk_f16_f32 v105, v98, v99
	v_cvt_pk_f16_f32 v106, v100, v101
	v_cvt_pk_f16_f32 v107, v102, v103
	v_add_u32_e32 v238, 0x400000, v236
	global_store_dwordx2 v238, v[104:105], s[28:29]
	global_store_dwordx2 v238, v[106:107], s[28:29] offset:32
	v_add_u32_e32 v235, 0x6000, v234
	global_load_dwordx4 v[64:67], v235, s[26:27] offset:0
	global_load_dwordx4 v[68:71], v235, s[26:27] offset:64
	global_load_dwordx4 v[72:75], v235, s[26:27] offset:128
	global_load_dwordx4 v[76:79], v235, s[26:27] offset:192
	s_waitcnt vmcnt(6)
	v_mfma_f32_16x16x32_bf16 v[96:99], v[0:3], v[80:83], 0
	v_mfma_f32_16x16x32_bf16 v[96:99], v[4:7], v[84:87], v[96:99]
	v_mfma_f32_16x16x32_bf16 v[96:99], v[8:11], v[88:91], v[96:99]
	v_mfma_f32_16x16x32_bf16 v[96:99], v[12:15], v[92:95], v[96:99]
	v_mfma_f32_16x16x32_bf16 v[100:103], v[32:35], v[80:83], 0
	v_mfma_f32_16x16x32_bf16 v[100:103], v[36:39], v[84:87], v[100:103]
	v_mfma_f32_16x16x32_bf16 v[100:103], v[40:43], v[88:91], v[100:103]
	v_mfma_f32_16x16x32_bf16 v[100:103], v[44:47], v[92:95], v[100:103]
	s_nop 7
	s_nop 3
	v_cvt_pk_f16_f32 v104, v96, v97
	v_cvt_pk_f16_f32 v105, v98, v99
	v_cvt_pk_f16_f32 v106, v100, v101
	v_cvt_pk_f16_f32 v107, v102, v103
	v_add_u32_e32 v238, 0x500000, v236
	global_store_dwordx2 v238, v[104:105], s[28:29]
	global_store_dwordx2 v238, v[106:107], s[28:29] offset:32
	v_add_u32_e32 v235, 0x7000, v234
	global_load_dwordx4 v[80:83], v235, s[26:27] offset:0
	global_load_dwordx4 v[84:87], v235, s[26:27] offset:64
	global_load_dwordx4 v[88:91], v235, s[26:27] offset:128
	global_load_dwordx4 v[92:95], v235, s[26:27] offset:192
	s_waitcnt vmcnt(6)
	v_mfma_f32_16x16x32_bf16 v[96:99], v[0:3], v[64:67], 0
	v_mfma_f32_16x16x32_bf16 v[96:99], v[4:7], v[68:71], v[96:99]
	v_mfma_f32_16x16x32_bf16 v[96:99], v[8:11], v[72:75], v[96:99]
	v_mfma_f32_16x16x32_bf16 v[96:99], v[12:15], v[76:79], v[96:99]
	v_mfma_f32_16x16x32_bf16 v[100:103], v[32:35], v[64:67], 0
	v_mfma_f32_16x16x32_bf16 v[100:103], v[36:39], v[68:71], v[100:103]
	v_mfma_f32_16x16x32_bf16 v[100:103], v[40:43], v[72:75], v[100:103]
	v_mfma_f32_16x16x32_bf16 v[100:103], v[44:47], v[76:79], v[100:103]
	s_nop 7
	s_nop 3
	v_cvt_pk_f16_f32 v104, v96, v97
	v_cvt_pk_f16_f32 v105, v98, v99
	v_cvt_pk_f16_f32 v106, v100, v101
	v_cvt_pk_f16_f32 v107, v102, v103
	v_add_u32_e32 v238, 0x600000, v236
	global_store_dwordx2 v238, v[104:105], s[28:29]
	global_store_dwordx2 v238, v[106:107], s[28:29] offset:32
	v_add_u32_e32 v235, 0x8000, v234
	global_load_dwordx4 v[64:67], v235, s[26:27] offset:0
	global_load_dwordx4 v[68:71], v235, s[26:27] offset:64
	global_load_dwordx4 v[72:75], v235, s[26:27] offset:128
	global_load_dwordx4 v[76:79], v235, s[26:27] offset:192
	s_waitcnt vmcnt(6)
	v_mfma_f32_16x16x32_bf16 v[96:99], v[0:3], v[80:83], 0
	v_mfma_f32_16x16x32_bf16 v[96:99], v[4:7], v[84:87], v[96:99]
	v_mfma_f32_16x16x32_bf16 v[96:99], v[8:11], v[88:91], v[96:99]
	v_mfma_f32_16x16x32_bf16 v[96:99], v[12:15], v[92:95], v[96:99]
	v_mfma_f32_16x16x32_bf16 v[100:103], v[32:35], v[80:83], 0
	v_mfma_f32_16x16x32_bf16 v[100:103], v[36:39], v[84:87], v[100:103]
	v_mfma_f32_16x16x32_bf16 v[100:103], v[40:43], v[88:91], v[100:103]
	v_mfma_f32_16x16x32_bf16 v[100:103], v[44:47], v[92:95], v[100:103]
	s_nop 7
	s_nop 3
	v_cvt_pk_f16_f32 v104, v96, v97
	v_cvt_pk_f16_f32 v105, v98, v99
	v_cvt_pk_f16_f32 v106, v100, v101
	v_cvt_pk_f16_f32 v107, v102, v103
	v_add_u32_e32 v238, 0x700000, v236
	global_store_dwordx2 v238, v[104:105], s[28:29]
	global_store_dwordx2 v238, v[106:107], s[28:29] offset:32
	v_add_u32_e32 v235, 0x9000, v234
	global_load_dwordx4 v[80:83], v235, s[26:27] offset:0
	global_load_dwordx4 v[84:87], v235, s[26:27] offset:64
	global_load_dwordx4 v[88:91], v235, s[26:27] offset:128
	global_load_dwordx4 v[92:95], v235, s[26:27] offset:192
	s_waitcnt vmcnt(6)
; DI void phase9(const Params& P, char* smem) {
;     ...
;     const int brow = (tile >> 4) * 128, hc = tile & 15;
;     gemm_tile<false>(Qp + (long)brow * 2048 + hc * 128, 2048, SKb + (long)hc * 128 * 128, 128, 0, 2, 0, 0, smem, [&](int row0, int col, f32x4 v) {
;       typedef _Float16 h4 __attribute__((ext_vector_type(4)));
;       h4 hv; hv[0] = (_Float16)v[0]; hv[1] = (_Float16)v[1]; hv[2] = (_Float16)v[2]; hv[3] = (_Float16)v[3];
;       *reinterpret_cast<h4*>(ST + ((long)(hc * 128 + col)) * NTOK + brow + row0) = hv;
;     });
	v_mfma_f32_16x16x32_bf16 v[96:99], v[16:19], v[64:67], 0
	v_mfma_f32_16x16x32_bf16 v[96:99], v[20:23], v[68:71], v[96:99]
	v_mfma_f32_16x16x32_bf16 v[96:99], v[24:27], v[72:75], v[96:99]
	v_mfma_f32_16x16x32_bf16 v[96:99], v[28:31], v[76:79], v[96:99]
	v_mfma_f32_16x16x32_bf16 v[100:103], v[48:51], v[64:67], 0
	v_mfma_f32_16x16x32_bf16 v[100:103], v[52:55], v[68:71], v[100:103]
	v_mfma_f32_16x16x32_bf16 v[100:103], v[56:59], v[72:75], v[100:103]
	v_mfma_f32_16x16x32_bf16 v[100:103], v[60:63], v[76:79], v[100:103]
	s_nop 7
	s_nop 3
	v_cvt_pk_f16_f32 v104, v96, v97
	v_cvt_pk_f16_f32 v105, v98, v99
	v_cvt_pk_f16_f32 v106, v100, v101
	v_cvt_pk_f16_f32 v107, v102, v103
	v_add_u32_e32 v238, 0x800000, v236
	global_store_dwordx2 v238, v[104:105], s[28:29]
	global_store_dwordx2 v238, v[106:107], s[28:29] offset:32
	v_add_u32_e32 v235, 0xa000, v234
	global_load_dwordx4 v[64:67], v235, s[26:27] offset:0
	global_load_dwordx4 v[68:71], v235, s[26:27] offset:64
	global_load_dwordx4 v[72:75], v235, s[26:27] offset:128
	global_load_dwordx4 v[76:79], v235, s[26:27] offset:192
	s_waitcnt vmcnt(6)
	v_mfma_f32_16x16x32_bf16 v[96:99], v[16:19], v[80:83], 0
	v_mfma_f32_16x16x32_bf16 v[96:99], v[20:23], v[84:87], v[96:99]
	v_mfma_f32_16x16x32_bf16 v[96:99], v[24:27], v[88:91], v[96:99]
	v_mfma_f32_16x16x32_bf16 v[96:99], v[28:31], v[92:95], v[96:99]
	v_mfma_f32_16x16x32_bf16 v[100:103], v[48:51], v[80:83], 0
	v_mfma_f32_16x16x32_bf16 v[100:103], v[52:55], v[84:87], v[100:103]
	v_mfma_f32_16x16x32_bf16 v[100:103], v[56:59], v[88:91], v[100:103]
	v_mfma_f32_16x16x32_bf16 v[100:103], v[60:63], v[92:95], v[100:103]
	s_nop 7
	s_nop 3
	v_cvt_pk_f16_f32 v104, v96, v97
	v_cvt_pk_f16_f32 v105, v98, v99
	v_cvt_pk_f16_f32 v106, v100, v101
	v_cvt_pk_f16_f32 v107, v102, v103
	v_add_u32_e32 v238, 0x900000, v236
	global_store_dwordx2 v238, v[104:105], s[28:29]
	global_store_dwordx2 v238, v[106:107], s[28:29] offset:32
	v_add_u32_e32 v235, 0xb000, v234
	global_load_dwordx4 v[80:83], v235, s[26:27] offset:0
	global_load_dwordx4 v[84:87], v235, s[26:27] offset:64
	global_load_dwordx4 v[88:91], v235, s[26:27] offset:128
	global_load_dwordx4 v[92:95], v235, s[26:27] offset:192
	s_waitcnt vmcnt(6)
	v_mfma_f32_16x16x32_bf16 v[96:99], v[16:19], v[64:67], 0
	v_mfma_f32_16x16x32_bf16 v[96:99], v[20:23], v[68:71], v[96:99]
	v_mfma_f32_16x16x32_bf16 v[96:99], v[24:27], v[72:75], v[96:99]
	v_mfma_f32_16x16x32_bf16 v[96:99], v[28:31], v[76:79], v[96:99]
	v_mfma_f32_16x16x32_bf16 v[100:103], v[48:51], v[64:67], 0
	v_mfma_f32_16x16x32_bf16 v[100:103], v[52:55], v[68:71], v[100:103]
	v_mfma_f32_16x16x32_bf16 v[100:103], v[56:59], v[72:75], v[100:103]
	v_mfma_f32_16x16x32_bf16 v[100:103], v[60:63], v[76:79], v[100:103]
	s_nop 7
	s_nop 3
	v_cvt_pk_f16_f32 v104, v96, v97
	v_cvt_pk_f16_f32 v105, v98, v99
	v_cvt_pk_f16_f32 v106, v100, v101
	v_cvt_pk_f16_f32 v107, v102, v103
	v_add_u32_e32 v238, 0xa00000, v236
	global_store_dwordx2 v238, v[104:105], s[28:29]
	global_store_dwordx2 v238, v[106:107], s[28:29] offset:32
	v_add_u32_e32 v235, 0xc000, v234
	global_load_dwordx4 v[64:67], v235, s[26:27] offset:0
	global_load_dwordx4 v[68:71], v235, s[26:27] offset:64
	global_load_dwordx4 v[72:75], v235, s[26:27] offset:128
	global_load_dwordx4 v[76:79], v235, s[26:27] offset:192
	s_waitcnt vmcnt(6)
	v_mfma_f32_16x16x32_bf16 v[96:99], v[16:19], v[80:83], 0
	v_mfma_f32_16x16x32_bf16 v[96:99], v[20:23], v[84:87], v[96:99]
	v_mfma_f32_16x16x32_bf16 v[96:99], v[24:27], v[88:91], v[96:99]
	v_mfma_f32_16x16x32_bf16 v[96:99], v[28:31], v[92:95], v[96:99]
	v_mfma_f32_16x16x32_bf16 v[100:103], v[48:51], v[80:83], 0
	v_mfma_f32_16x16x32_bf16 v[100:103], v[52:55], v[84:87], v[100:103]
	v_mfma_f32_16x16x32_bf16 v[100:103], v[56:59], v[88:91], v[100:103]
	v_mfma_f32_16x16x32_bf16 v[100:103], v[60:63], v[92:95], v[100:103]
	s_nop 7
	s_nop 3
	v_cvt_pk_f16_f32 v104, v96, v97
	v_cvt_pk_f16_f32 v105, v98, v99
	v_cvt_pk_f16_f32 v106, v100, v101
	v_cvt_pk_f16_f32 v107, v102, v103
	v_add_u32_e32 v238, 0xb00000, v236
	global_store_dwordx2 v238, v[104:105], s[28:29]
	global_store_dwordx2 v238, v[106:107], s[28:29] offset:32
	v_add_u32_e32 v235, 0xd000, v234
	global_load_dwordx4 v[80:83], v235, s[26:27] offset:0
	global_load_dwordx4 v[84:87], v235, s[26:27] offset:64
	global_load_dwordx4 v[88:91], v235, s[26:27] offset:128
	global_load_dwordx4 v[92:95], v235, s[26:27] offset:192
	s_waitcnt vmcnt(6)
; DI void phase9(const Params& P, char* smem) {
;     ...
;     const int brow = (tile >> 4) * 128, hc = tile & 15;
;     gemm_tile<false>(Qp + (long)brow * 2048 + hc * 128, 2048, SKb + (long)hc * 128 * 128, 128, 0, 2, 0, 0, smem, [&](int row0, int col, f32x4 v) {
;       typedef _Float16 h4 __attribute__((ext_vector_type(4)));
;       h4 hv; hv[0] = (_Float16)v[0]; hv[1] = (_Float16)v[1]; hv[2] = (_Float16)v[2]; hv[3] = (_Float16)v[3];
;       *reinterpret_cast<h4*>(ST + ((long)(hc * 128 + col)) * NTOK + brow + row0) = hv;
;     });
	v_mfma_f32_16x16x32_bf16 v[96:99], v[16:19], v[64:67], 0
	v_mfma_f32_16x16x32_bf16 v[96:99], v[20:23], v[68:71], v[96:99]
	v_mfma_f32_16x16x32_bf16 v[96:99], v[24:27], v[72:75], v[96:99]
	v_mfma_f32_16x16x32_bf16 v[96:99], v[28:31], v[76:79], v[96:99]
	v_mfma_f32_16x16x32_bf16 v[100:103], v[48:51], v[64:67], 0
	v_mfma_f32_16x16x32_bf16 v[100:103], v[52:55], v[68:71], v[100:103]
	v_mfma_f32_16x16x32_bf16 v[100:103], v[56:59], v[72:75], v[100:103]
	v_mfma_f32_16x16x32_bf16 v[100:103], v[60:63], v[76:79], v[100:103]
	s_nop 7
	s_nop 3
	v_cvt_pk_f16_f32 v104, v96, v97
	v_cvt_pk_f16_f32 v105, v98, v99
	v_cvt_pk_f16_f32 v106, v100, v101
	v_cvt_pk_f16_f32 v107, v102, v103
	v_add_u32_e32 v238, 0xc00000, v236
	global_store_dwordx2 v238, v[104:105], s[28:29]
	global_store_dwordx2 v238, v[106:107], s[28:29] offset:32
	v_add_u32_e32 v235, 0xe000, v234
	global_load_dwordx4 v[64:67], v235, s[26:27] offset:0
	global_load_dwordx4 v[68:71], v235, s[26:27] offset:64
	global_load_dwordx4 v[72:75], v235, s[26:27] offset:128
	global_load_dwordx4 v[76:79], v235, s[26:27] offset:192
	s_waitcnt vmcnt(6)
	v_mfma_f32_16x16x32_bf16 v[96:99], v[16:19], v[80:83], 0
	v_mfma_f32_16x16x32_bf16 v[96:99], v[20:23], v[84:87], v[96:99]
	v_mfma_f32_16x16x32_bf16 v[96:99], v[24:27], v[88:91], v[96:99]
	v_mfma_f32_16x16x32_bf16 v[96:99], v[28:31], v[92:95], v[96:99]
	v_mfma_f32_16x16x32_bf16 v[100:103], v[48:51], v[80:83], 0
	v_mfma_f32_16x16x32_bf16 v[100:103], v[52:55], v[84:87], v[100:103]
	v_mfma_f32_16x16x32_bf16 v[100:103], v[56:59], v[88:91], v[100:103]
	v_mfma_f32_16x16x32_bf16 v[100:103], v[60:63], v[92:95], v[100:103]
	s_nop 7
	s_nop 3
	v_cvt_pk_f16_f32 v104, v96, v97
	v_cvt_pk_f16_f32 v105, v98, v99
	v_cvt_pk_f16_f32 v106, v100, v101
	v_cvt_pk_f16_f32 v107, v102, v103
	v_add_u32_e32 v238, 0xd00000, v236
	global_store_dwordx2 v238, v[104:105], s[28:29]
	global_store_dwordx2 v238, v[106:107], s[28:29] offset:32
	v_add_u32_e32 v235, 0xf000, v234
	global_load_dwordx4 v[80:83], v235, s[26:27] offset:0
	global_load_dwordx4 v[84:87], v235, s[26:27] offset:64
	global_load_dwordx4 v[88:91], v235, s[26:27] offset:128
	global_load_dwordx4 v[92:95], v235, s[26:27] offset:192
	s_waitcnt vmcnt(6)
	v_mfma_f32_16x16x32_bf16 v[96:99], v[16:19], v[64:67], 0
	v_mfma_f32_16x16x32_bf16 v[96:99], v[20:23], v[68:71], v[96:99]
	v_mfma_f32_16x16x32_bf16 v[96:99], v[24:27], v[72:75], v[96:99]
	v_mfma_f32_16x16x32_bf16 v[96:99], v[28:31], v[76:79], v[96:99]
	v_mfma_f32_16x16x32_bf16 v[100:103], v[48:51], v[64:67], 0
	v_mfma_f32_16x16x32_bf16 v[100:103], v[52:55], v[68:71], v[100:103]
	v_mfma_f32_16x16x32_bf16 v[100:103], v[56:59], v[72:75], v[100:103]
	v_mfma_f32_16x16x32_bf16 v[100:103], v[60:63], v[76:79], v[100:103]
	s_nop 7
	s_nop 3
	v_cvt_pk_f16_f32 v104, v96, v97
	v_cvt_pk_f16_f32 v105, v98, v99
	v_cvt_pk_f16_f32 v106, v100, v101
	v_cvt_pk_f16_f32 v107, v102, v103
	v_add_u32_e32 v238, 0xe00000, v236
	global_store_dwordx2 v238, v[104:105], s[28:29]
	global_store_dwordx2 v238, v[106:107], s[28:29] offset:32
	s_waitcnt vmcnt(2)
	v_mfma_f32_16x16x32_bf16 v[96:99], v[16:19], v[80:83], 0
	v_mfma_f32_16x16x32_bf16 v[96:99], v[20:23], v[84:87], v[96:99]
	v_mfma_f32_16x16x32_bf16 v[96:99], v[24:27], v[88:91], v[96:99]
	v_mfma_f32_16x16x32_bf16 v[96:99], v[28:31], v[92:95], v[96:99]
	v_mfma_f32_16x16x32_bf16 v[100:103], v[48:51], v[80:83], 0
	v_mfma_f32_16x16x32_bf16 v[100:103], v[52:55], v[84:87], v[100:103]
	v_mfma_f32_16x16x32_bf16 v[100:103], v[56:59], v[88:91], v[100:103]
	v_mfma_f32_16x16x32_bf16 v[100:103], v[60:63], v[92:95], v[100:103]
	s_nop 7
	s_nop 3
	v_cvt_pk_f16_f32 v104, v96, v97
	v_cvt_pk_f16_f32 v105, v98, v99
	v_cvt_pk_f16_f32 v106, v100, v101
	v_cvt_pk_f16_f32 v107, v102, v103
	v_add_u32_e32 v238, 0xf00000, v236
	global_store_dwordx2 v238, v[104:105], s[28:29]
	global_store_dwordx2 v238, v[106:107], s[28:29] offset:32
	s_barrier
	s_add_i32 s75, s75, s5
	s_add_i32 s6, s6, s8
	s_cmpk_lt_i32 s75, 0x80
	s_cbranch_scc1 .LBB0_1068

; #define TILE_LOOP(tile, N, C)                                                                                          \
;   for (int q0_ = (RBLK >> 3) * 2, tile = 0;                                                                            \
;        q0_ < (N) / 8 && ((tile = xcd_tile((q0_ + VHALF < (N) / 8 ? q0_ + VHALF : q0_), RBLK & 7, (C))), true);          \
;        q0_ += (RGRID >> 3) * 2)
; DI void phase9(const Params& P, char* smem) {
;     ...
;   TILE_LOOP(tile, 256 * 16, 16) {
;     const int brow = (tile >> 4) * 128, hc = tile & 15;
;     gemm_tile<false>(Qp + (long)brow * 2048 + hc * 128, 2048, SKb + (long)hc * 128 * 128, 128, 0, 2, 0, 0, smem, [&](int row0, int col, f32x4 v) {
.LBB0_1123:
	s_or_b64 exec, exec, s[0:1]
	s_cmpk_gt_i32 s64, 0x1ff
	s_waitcnt lgkmcnt(0)
	s_barrier
	s_branch .LBB0_1126
	v_xor_b32_e32 v2, v193, v189
	v_or_b32_e32 v8, 0x100, v191
	v_or_b32_e32 v12, 0x200, v191
	v_or_b32_e32 v16, 0x300, v189
	v_and_b32_e32 v18, 64, v174
	v_lshlrev_b32_e32 v2, 3, v2
	v_lshlrev_b32_e32 v21, 4, v8
	v_lshlrev_b32_e32 v22, 4, v12
	v_lshlrev_b32_e32 v23, 4, v16
	v_and_or_b32 v19, v189, 15, v18
	v_bitop3_b32 v20, v193, v170, 3 bitop3:0x6c
	s_add_u32 s0, s78, 0x18a80000
	v_mov_b32_e32 v3, 0
	v_and_b32_e32 v2, 56, v2
	v_lshrrev_b32_e32 v9, 3, v8
	v_lshrrev_b32_e32 v13, 3, v12
	v_lshrrev_b32_e32 v17, 3, v16
	v_lshl_add_u32 v42, v20, 4, v192
	v_lshlrev_b32_e32 v43, 7, v19
	v_and_b32_e32 v44, 0x2780, v171
	v_lshl_add_u32 v45, v173, 4, v192
	v_lshl_or_b32 v20, v169, 2, v18
	s_movk_i32 s4, 0x4f
	v_add_u32_e32 v25, v192, v168
	v_add_u32_e32 v27, v192, v21
	v_add_u32_e32 v29, v192, v22
	v_add_u32_e32 v31, v192, v23
	s_addc_u32 s1, s79, 0
	s_and_b32 s2, s3, 14
	v_lshlrev_b32_e32 v0, 12, v175
	v_mov_b32_e32 v1, v3
	v_lshlrev_b32_e32 v4, 8, v175
	v_mov_b32_e32 v5, v3
	v_lshlrev_b32_e32 v6, 12, v9
	v_mov_b32_e32 v7, v3
	v_lshlrev_b32_e32 v8, 8, v9
	v_mov_b32_e32 v9, v3
	s_movk_i32 s3, 0x200
	v_lshlrev_b32_e32 v10, 12, v13
	v_mov_b32_e32 v11, v3
	v_lshlrev_b32_e32 v12, 8, v13
	v_mov_b32_e32 v13, v3
	v_lshlrev_b32_e32 v14, 12, v17
	v_mov_b32_e32 v15, v3
	v_lshlrev_b32_e32 v16, 8, v17
	v_mov_b32_e32 v17, v3
	v_and_b32_sdwa v24, v189, s4 dst_sel:WORD_1 dst_unused:UNUSED_PAD src0_sel:DWORD src1_sel:DWORD
	v_lshlrev_b32_e32 v18, 1, v2
	v_mov_b32_e32 v19, v3
	v_add_u32_e32 v26, 0x4000, v25
	v_add_u32_e32 v28, 0x4000, v27
	v_add_u32_e32 v30, 0x4000, v29
	v_add_u32_e32 v32, 0x4000, v31
	s_mov_b64 s[6:7], 0x80
	v_add_u32_e32 v33, 0x8000, v25
	v_add_u32_e32 v34, 0xc000, v25
	v_add_u32_e32 v35, 0x8000, v27
	v_add_u32_e32 v36, 0xc000, v27
	v_lshlrev_b32_e32 v20, 1, v20
	v_mov_b32_e32 v21, v3
	s_mov_b64 s[10:11], 0x100000
	s_mov_b32 s4, 0x100000
	s_mov_b64 s[12:13], 0x200000
	s_mov_b32 s5, 0x200000
	s_mov_b64 s[14:15], 0x300000
	s_mov_b32 s8, 0x300000
	v_add_u32_e32 v37, 0x8000, v29
	v_add_u32_e32 v38, 0xc000, v29
	v_add_u32_e32 v39, 0x8000, v31
	v_add_u32_e32 v40, 0xc000, v31
	v_add_u32_e32 v41, v42, v43
	v_add_u32_e32 v42, v42, v44
	v_add_u32_e32 v43, v45, v43
	v_add_u32_e32 v44, v45, v44

; DI void topk_half(const _Float16* __restrict__ sp, unsigned (&R)[16]) {
; #pragma unroll
;   for (int e = 0; e < 16; ++e) R[e] = 0u;
; #pragma unroll 1
;   for (int gi = 0; gi < 8; ++gi) {
;     unsigned Gk[16];
; #pragma unroll
;     for (int e = 0; e < 16; ++e) {
;       const int n = gi * 16 + e;
;       const unsigned bits = __builtin_bit_cast(unsigned short, sp[(long)n * NTOK]);
;       const unsigned o = (bits & 0x8000u) ? (~bits & 0xffffu) : (bits | 0x8000u);
;       Gk[e] = (o << 16) | (unsigned)(127 - n);
;     }
;     SORT16(Gk)
;     MERGE16(R, Gk)
;   }
; }
.LBB0_1183:
	v_alignbit_b32 v1, v129, v128, 15
	v_lshlrev_b32_e32 v4, 1, v1
	v_ashrrev_i32_e32 v5, 31, v4
	v_lshlrev_b64 v[4:5], 23, v[4:5]
	v_and_b32_e32 v1, 0x7fff, v26
	v_lshrrev_b64 v[2:3], 15, v[128:129]
	v_lshl_or_b32 v4, v1, 1, v4
	v_lshl_add_u64 v[6:7], s[40:41], 0, v[4:5]
	s_movk_i32 s91, 0x70
	v_mov_b32_e32 v35, 0
	v_mov_b32_e32 v24, 0
	v_mov_b32_e32 v40, 0
	v_mov_b32_e32 v41, 0
	v_mov_b32_e32 v39, 0
	v_mov_b32_e32 v25, 0
	v_mov_b32_e32 v38, 0
	v_mov_b32_e32 v36, 0
	v_mov_b32_e32 v33, 0
	v_mov_b32_e32 v32, 0
	v_mov_b32_e32 v31, 0
	v_mov_b32_e32 v30, 0
	v_mov_b32_e32 v3, 0
	v_mov_b32_e32 v1, 0
	v_mov_b32_e32 v34, 0
	v_mov_b32_e32 v37, 0
	v_lshrrev_b32_e32 v88, 3, v208
	v_and_b32_e32 v89, 7, v208
	v_lshlrev_b32_e32 v88, 16, v88
	v_lshl_add_u32 v88, v89, 4, v88
	v_lshlrev_b32_e32 v89, 1, v208
	v_sub_u32_e32 v88, v88, v89
	v_add_u32_e32 v86, v4, v88
	v_mov_b32_e32 v144, 0x6000000
	v_cmp_le_u32_e32 vcc, 0x4000000, v4
	s_add_u32 s36, s78, 0xa000000
	s_addc_u32 s37, s79, 0
	v_cndmask_b32_e32 v144, 0, v144, vcc
	v_add_u32_e32 v86, v86, v144
	v_and_b32_e32 v100, 0x3c00, v209
	v_lshlrev_b32_e32 v100, 1, v100
	v_add_u32_e32 v101, v100, v89
	v_lshl_add_u32 v100, v208, 4, v100
	global_load_dwordx4 v[90:93], v86, s[36:37]
	v_add_u32_e32 v87, 0x80000, v86
	global_load_dwordx4 v[94:97], v87, s[36:37]
	v_add_u32_e32 v86, 0x100000, v86
.LBB0_1184:
	s_waitcnt vmcnt(0)
	ds_write_b128 v100, v[90:93]
	ds_write_b128 v100, v[94:97] offset:1024
	s_waitcnt lgkmcnt(0)
	global_load_dwordx4 v[90:93], v86, s[36:37]
	v_add_u32_e32 v87, 0x80000, v86
	global_load_dwordx4 v[94:97], v87, s[36:37]
	v_add_u32_e32 v86, 0x100000, v86
	ds_read_u16 v42, v101
	ds_read_u16 v47, v101 offset:128
	ds_read_u16 v46, v101 offset:256
	ds_read_u16 v45, v101 offset:384
	ds_read_u16 v44, v101 offset:512
	ds_read_u16 v43, v101 offset:640
	ds_read_u16 v17, v101 offset:768
	ds_read_u16 v16, v101 offset:896
	ds_read_u16 v14, v101 offset:1024
	ds_read_u16 v13, v101 offset:1152
	ds_read_u16 v12, v101 offset:1280
	ds_read_u16 v11, v101 offset:1408
	ds_read_u16 v10, v101 offset:1536
	ds_read_u16 v9, v101 offset:1664
	ds_read_u16 v8, v101 offset:1792
	ds_read_u16 v15, v101 offset:1920
	s_waitcnt lgkmcnt(0)
	v_and_b32_e32 v18, 0xffff, v42
	v_bitop3_b32 v19, v18, s57, v18 bitop3:0xc
	v_or_b32_e32 v18, 0x8000, v18
	v_cmp_gt_i16_e32 vcc, 0, v42
	v_and_b32_e32 v20, 0xffff, v47
	v_and_b32_e32 v21, 0xffff, v46
	v_and_b32_e32 v22, 0xffff, v45
	v_and_b32_e32 v23, 0xffff, v44
	v_and_b32_e32 v48, 0xffff, v43
	v_and_b32_e32 v49, 0xffff, v17
	v_and_b32_e32 v50, 0xffff, v16
	v_and_b32_e32 v51, 0xffff, v14
	v_and_b32_e32 v52, 0xffff, v13
	v_and_b32_e32 v53, 0xffff, v12
	v_and_b32_e32 v54, 0xffff, v11
	v_and_b32_e32 v55, 0xffff, v10
	v_and_b32_e32 v56, 0xffff, v9
	v_and_b32_e32 v57, 0xffff, v8
	v_and_b32_e32 v58, 0xffff, v15
	v_cndmask_b32_e32 v18, v18, v19, vcc
	v_bitop3_b32 v19, v20, s57, v20 bitop3:0xc
	v_or_b32_e32 v20, 0x8000, v20
	v_cmp_gt_i16_e32 vcc, 0, v47
	v_bitop3_b32 v42, v21, s57, v21 bitop3:0xc
	v_or_b32_e32 v21, 0x8000, v21
	v_cmp_gt_i16_e64 s[0:1], 0, v46
	v_bitop3_b32 v46, v22, s57, v22 bitop3:0xc
	v_or_b32_e32 v22, 0x8000, v22
	v_cmp_gt_i16_e64 s[6:7], 0, v45
	v_bitop3_b32 v45, v23, s57, v23 bitop3:0xc
	v_or_b32_e32 v23, 0x8000, v23
	v_cmp_gt_i16_e64 s[8:9], 0, v44
	v_bitop3_b32 v44, v48, s57, v48 bitop3:0xc
	v_or_b32_e32 v47, 0x8000, v48
	v_cmp_gt_i16_e64 s[10:11], 0, v43
	v_bitop3_b32 v43, v49, s57, v49 bitop3:0xc
	v_or_b32_e32 v48, 0x8000, v49
	v_cmp_gt_i16_e64 s[12:13], 0, v17
	v_bitop3_b32 v17, v50, s57, v50 bitop3:0xc
	v_or_b32_e32 v49, 0x8000, v50
	v_cmp_gt_i16_e64 s[14:15], 0, v16
	v_bitop3_b32 v16, v51, s57, v51 bitop3:0xc
	v_or_b32_e32 v50, 0x8000, v51
	v_cmp_gt_i16_e64 s[16:17], 0, v14
	v_bitop3_b32 v14, v52, s57, v52 bitop3:0xc
	v_or_b32_e32 v51, 0x8000, v52
	v_cmp_gt_i16_e64 s[18:19], 0, v13
	v_bitop3_b32 v13, v53, s57, v53 bitop3:0xc
	v_or_b32_e32 v52, 0x8000, v53
	v_cmp_gt_i16_e64 s[20:21], 0, v12
	v_bitop3_b32 v12, v54, s57, v54 bitop3:0xc
	v_or_b32_e32 v53, 0x8000, v54
	v_cmp_gt_i16_e64 s[24:25], 0, v11
	v_bitop3_b32 v11, v55, s57, v55 bitop3:0xc
	v_or_b32_e32 v54, 0x8000, v55
	v_cmp_gt_i16_e64 s[26:27], 0, v10
	v_bitop3_b32 v10, v56, s57, v56 bitop3:0xc
	v_or_b32_e32 v55, 0x8000, v56
	v_cmp_gt_i16_e64 s[28:29], 0, v9
	v_bitop3_b32 v9, v57, s57, v57 bitop3:0xc
	v_or_b32_e32 v56, 0x8000, v57
	v_cmp_gt_i16_e64 s[30:31], 0, v8
	v_bitop3_b32 v8, v58, s57, v58 bitop3:0xc
	v_or_b32_e32 v57, 0x8000, v58
	v_cmp_gt_i16_e64 s[34:35], 0, v15
	v_lshlrev_b32_e32 v15, 16, v18
	v_cndmask_b32_e32 v18, v20, v19, vcc
	v_cndmask_b32_e64 v19, v21, v42, s[0:1]
	v_cndmask_b32_e64 v20, v22, v46, s[6:7]
	v_cndmask_b32_e64 v21, v23, v45, s[8:9]
	v_cndmask_b32_e64 v22, v47, v44, s[10:11]
	v_cndmask_b32_e64 v23, v48, v43, s[12:13]
	v_cndmask_b32_e64 v17, v49, v17, s[14:15]
	v_cndmask_b32_e64 v16, v50, v16, s[16:17]
	v_cndmask_b32_e64 v14, v51, v14, s[18:19]
	v_cndmask_b32_e64 v13, v52, v13, s[20:21]
	v_cndmask_b32_e64 v12, v53, v12, s[24:25]
	v_cndmask_b32_e64 v11, v54, v11, s[26:27]
	v_cndmask_b32_e64 v10, v55, v10, s[28:29]
	v_cndmask_b32_e64 v9, v56, v9, s[30:31]
	v_cndmask_b32_e64 v8, v57, v8, s[34:35]
	v_lshlrev_b32_e32 v18, 16, v18
	v_lshlrev_b32_e32 v19, 16, v19
	v_lshlrev_b32_e32 v20, 16, v20
	v_lshlrev_b32_e32 v21, 16, v21
	v_lshlrev_b32_e32 v22, 16, v22
	v_lshlrev_b32_e32 v23, 16, v23
	v_lshlrev_b32_e32 v17, 16, v17
	v_lshlrev_b32_e32 v16, 16, v16
	v_lshlrev_b32_e32 v14, 16, v14
	v_lshlrev_b32_e32 v13, 16, v13
	v_lshlrev_b32_e32 v12, 16, v12
	v_lshlrev_b32_e32 v11, 16, v11
	v_lshlrev_b32_e32 v10, 16, v10
	v_lshlrev_b32_e32 v9, 16, v9
	v_add3_u32 v15, s91, v15, 15
	v_lshl_add_u32 v8, v8, 16, s91
; DI void topk_half(const _Float16* __restrict__ sp, unsigned (&R)[16]) {
; #pragma unroll
;   for (int e = 0; e < 16; ++e) R[e] = 0u;
; #pragma unroll 1
;   for (int gi = 0; gi < 8; ++gi) {
;     unsigned Gk[16];
; #pragma unroll
;     for (int e = 0; e < 16; ++e) {
;       const int n = gi * 16 + e;
;       const unsigned bits = __builtin_bit_cast(unsigned short, sp[(long)n * NTOK]);
;       const unsigned o = (bits & 0x8000u) ? (~bits & 0xffffu) : (bits | 0x8000u);
;       Gk[e] = (o << 16) | (unsigned)(127 - n);
;     }
;     SORT16(Gk)
;     MERGE16(R, Gk)
	v_add3_u32 v18, s91, v18, 14
	v_add3_u32 v19, s91, v19, 13
	v_add3_u32 v20, s91, v20, 12
	v_add3_u32 v21, s91, v21, 11
	v_add3_u32 v22, s91, v22, 10
	v_add3_u32 v23, s91, v23, 9
	v_add3_u32 v17, s91, v17, 8
	v_add3_u32 v16, s91, v16, 7
	v_add3_u32 v14, s91, v14, 6
	v_add3_u32 v13, s91, v13, 5
	v_add3_u32 v12, s91, v12, 4
	v_add3_u32 v11, s91, v11, 3
	v_add3_u32 v10, s91, v10, 2
	v_add3_u32 v9, s91, v9, 1
	v_max_u32_e32 v42, v15, v18
	v_min_u32_e32 v15, v15, v18
	v_max_u32_e32 v18, v19, v20
	v_min_u32_e32 v19, v19, v20
	v_max_u32_e32 v20, v21, v22
	v_min_u32_e32 v21, v21, v22
	v_max_u32_e32 v22, v23, v17
	v_min_u32_e32 v17, v23, v17
	v_max_u32_e32 v23, v16, v14
	v_min_u32_e32 v14, v16, v14
	v_max_u32_e32 v16, v13, v12
	v_min_u32_e32 v12, v13, v12
	v_max_u32_e32 v13, v11, v10
	v_min_u32_e32 v10, v11, v10
	v_max_u32_e32 v11, v9, v8
	v_min_u32_e32 v8, v9, v8
	v_max_u32_e32 v9, v42, v18
	v_min_u32_e32 v18, v42, v18
	v_max_u32_e32 v42, v15, v19
	v_min_u32_e32 v15, v15, v19
	v_max_u32_e32 v19, v20, v22
	v_min_u32_e32 v20, v20, v22
	v_max_u32_e32 v22, v21, v17
	v_min_u32_e32 v17, v21, v17
	v_max_u32_e32 v21, v23, v16
	v_min_u32_e32 v16, v23, v16
	v_max_u32_e32 v23, v14, v12
	v_min_u32_e32 v12, v14, v12
	v_max_u32_e32 v14, v13, v11
	v_min_u32_e32 v11, v13, v11
	v_max_u32_e32 v13, v10, v8
	v_min_u32_e32 v8, v10, v8
	v_max_u32_e32 v10, v42, v18
	v_min_u32_e32 v18, v42, v18
	v_max_u32_e32 v42, v22, v20
	v_min_u32_e32 v20, v22, v20
	v_max_u32_e32 v22, v23, v16
	v_min_u32_e32 v16, v23, v16
	v_max_u32_e32 v23, v13, v11
	v_min_u32_e32 v11, v13, v11
	v_max_u32_e32 v13, v9, v19
	v_min_u32_e32 v9, v9, v19
	v_max_u32_e32 v19, v15, v17
	v_min_u32_e32 v15, v15, v17
	v_max_u32_e32 v17, v21, v14
	v_min_u32_e32 v14, v21, v14
	v_max_u32_e32 v21, v12, v8
	v_min_u32_e32 v8, v12, v8
	v_max_u32_e32 v12, v10, v42
	v_min_u32_e32 v10, v10, v42
	v_max_u32_e32 v42, v18, v20
	v_min_u32_e32 v18, v18, v20
	v_max_u32_e32 v20, v22, v23
	v_min_u32_e32 v22, v22, v23
	v_max_u32_e32 v23, v16, v11
	v_min_u32_e32 v11, v16, v11
	v_min_u32_e32 v16, v13, v17
	v_max_u32_e32 v43, v15, v8
	v_min_u32_e32 v8, v15, v8
	v_max3_u32 v13, v37, v13, v17
	v_max_u32_e32 v15, v42, v9
	v_min_u32_e32 v9, v42, v9
	v_max_u32_e32 v17, v19, v10
	v_min_u32_e32 v10, v19, v10
	v_max_u32_e32 v19, v23, v14
	v_min_u32_e32 v14, v23, v14
	v_max_u32_e32 v23, v21, v22
	v_min_u32_e32 v21, v21, v22
	v_max_u32_e32 v22, v12, v15
	v_min_u32_e32 v12, v12, v15
	v_max_u32_e32 v15, v17, v9
	v_min_u32_e32 v9, v17, v9
	v_max_u32_e32 v17, v10, v18
	v_min_u32_e32 v10, v10, v18
	v_max_u32_e32 v18, v20, v19
	v_min_u32_e32 v19, v20, v19
	v_max_u32_e32 v20, v23, v14
	v_min_u32_e32 v14, v23, v14
	v_max_u32_e32 v23, v21, v11
	v_min_u32_e32 v11, v21, v11
	v_max_u32_e32 v21, v22, v18
	v_min_u32_e32 v18, v22, v18
	v_max_u32_e32 v22, v12, v19
	v_min_u32_e32 v12, v12, v19
	v_max_u32_e32 v19, v15, v20
	v_min_u32_e32 v15, v15, v20
	v_max_u32_e32 v20, v9, v14
	v_min_u32_e32 v9, v9, v14
	v_max_u32_e32 v14, v17, v23
	v_min_u32_e32 v17, v17, v23
	v_max_u32_e32 v23, v10, v11
	v_min_u32_e32 v10, v10, v11
	v_max_u32_e32 v11, v20, v16
	v_min_u32_e32 v16, v20, v16
	v_max_u32_e32 v20, v14, v18
	v_min_u32_e32 v14, v14, v18
	v_max_u32_e32 v18, v23, v12
	v_min_u32_e32 v12, v23, v12
	v_max_u32_e32 v23, v43, v15
	v_min_u32_e32 v15, v43, v15
	v_max_u32_e32 v8, v35, v8
	v_max_u32_e32 v35, v22, v11
	v_min_u32_e32 v11, v22, v11
	v_max_u32_e32 v22, v19, v20
	v_min_u32_e32 v19, v19, v20
	v_max_u32_e32 v20, v18, v16
	v_min_u32_e32 v16, v18, v16
	v_max_u32_e32 v18, v23, v14
	v_min_u32_e32 v14, v23, v14
	v_max_u32_e32 v23, v12, v9
	v_min_u32_e32 v9, v12, v9
	v_max_u32_e32 v12, v15, v17
	v_min_u32_e32 v15, v15, v17
	v_min_u32_e32 v17, v21, v35
	v_min_u32_e32 v37, v22, v11
	v_min_u32_e32 v42, v19, v20
	v_min_u32_e32 v43, v18, v16
	v_min_u32_e32 v44, v14, v23
	v_min_u32_e32 v45, v12, v9
	v_min_u32_e32 v46, v15, v10
	v_max3_u32 v10, v40, v15, v10
	v_max3_u32 v9, v39, v12, v9
	v_max3_u32 v12, v38, v14, v23
	v_max3_u32 v14, v33, v18, v16
	v_max3_u32 v15, v31, v19, v20
	v_max3_u32 v3, v3, v22, v11
	v_max3_u32 v11, v34, v21, v35
	v_max_u32_e32 v16, v24, v46
	v_max_u32_e32 v18, v41, v45
	v_max_u32_e32 v19, v25, v44
	v_max_u32_e32 v20, v36, v43
	v_max_u32_e32 v21, v32, v42
	v_max_u32_e32 v22, v30, v37
	v_max_u32_e32 v1, v1, v17
	v_max_u32_e32 v17, v8, v14
	v_min_u32_e32 v8, v8, v14
	v_max_u32_e32 v14, v10, v15
	v_min_u32_e32 v10, v10, v15
	v_max_u32_e32 v15, v9, v3
	v_min_u32_e32 v3, v9, v3
	v_max_u32_e32 v9, v12, v11
	v_min_u32_e32 v11, v12, v11
	v_max_u32_e32 v12, v16, v21
	v_min_u32_e32 v16, v16, v21
	v_max_u32_e32 v21, v18, v22
	v_min_u32_e32 v18, v18, v22
	v_max_u32_e32 v22, v19, v1
	v_min_u32_e32 v1, v19, v1
	v_max_u32_e32 v19, v20, v13
	v_min_u32_e32 v13, v20, v13
	v_max_u32_e32 v20, v17, v15
	v_min_u32_e32 v15, v17, v15
	v_max_u32_e32 v17, v14, v9
	v_min_u32_e32 v9, v14, v9
	v_max_u32_e32 v14, v8, v3
	v_min_u32_e32 v3, v8, v3
	v_max_u32_e32 v8, v10, v11
	v_min_u32_e32 v10, v10, v11
	v_max_u32_e32 v11, v12, v22
	v_min_u32_e32 v12, v12, v22
	v_max_u32_e32 v22, v21, v19
	v_min_u32_e32 v19, v21, v19
	v_max_u32_e32 v21, v16, v1
	v_min_u32_e32 v1, v16, v1
	v_max_u32_e32 v16, v18, v13
	v_min_u32_e32 v13, v18, v13
	s_add_i32 s91, s91, -16
	v_max_u32_e32 v18, v20, v17
	v_min_u32_e32 v17, v20, v17
	v_max_u32_e32 v20, v15, v9
	v_min_u32_e32 v9, v15, v9
	v_max_u32_e32 v15, v14, v8
	v_min_u32_e32 v8, v14, v8
	v_max_u32_e32 v14, v3, v10
	v_min_u32_e32 v10, v3, v10
	v_max_u32_e32 v3, v11, v22
	v_min_u32_e32 v11, v11, v22
	v_max_u32_e32 v22, v12, v19
	v_min_u32_e32 v12, v12, v19
	v_max_u32_e32 v19, v21, v16
	v_min_u32_e32 v16, v21, v16
	v_max_u32_e32 v21, v1, v13
	v_min_u32_e32 v13, v1, v13
	s_cmp_lg_u32 s91, -16
	v_max_u32_e32 v35, v18, v3
	v_min_u32_e32 v24, v18, v3
	v_max_u32_e32 v40, v17, v11
	v_min_u32_e32 v41, v17, v11
	v_max_u32_e32 v39, v20, v22
	v_min_u32_e32 v25, v20, v22
	v_max_u32_e32 v38, v9, v12
	v_min_u32_e32 v36, v9, v12
	v_max_u32_e32 v33, v15, v19
	v_min_u32_e32 v32, v15, v19
	v_max_u32_e32 v31, v8, v16
	v_min_u32_e32 v30, v8, v16
	v_max_u32_e32 v3, v14, v21
	v_min_u32_e32 v1, v14, v21
	v_max_u32_e32 v34, v10, v13
	v_min_u32_e32 v37, v10, v13
	s_cbranch_scc1 .LBB0_1184
	v_lshl_add_u64 v[4:5], s[46:47], 0, v[4:5]
	v_mov_b32_e32 v55, 0
	s_movk_i32 s91, 0x70
	v_mov_b32_e32 v49, 0
	v_mov_b32_e32 v54, 0
	v_mov_b32_e32 v46, 0
	v_mov_b32_e32 v52, 0
	v_mov_b32_e32 v45, 0
	v_mov_b32_e32 v53, 0
	v_mov_b32_e32 v44, 0
	v_mov_b32_e32 v50, 0
	v_mov_b32_e32 v43, 0
	v_mov_b32_e32 v51, 0
	v_mov_b32_e32 v42, 0
	v_mov_b32_e32 v47, 0
	v_mov_b32_e32 v23, 0
	v_mov_b32_e32 v48, 0
	v_mov_b32_e32 v56, 0
; DI void topk_half(const _Float16* __restrict__ sp, unsigned (&R)[16]) {
; #pragma unroll
;   for (int e = 0; e < 16; ++e) R[e] = 0u;
; #pragma unroll 1
;   for (int gi = 0; gi < 8; ++gi) {
;     unsigned Gk[16];
; #pragma unroll
;     for (int e = 0; e < 16; ++e) {
;       const int n = gi * 16 + e;
;       const unsigned bits = __builtin_bit_cast(unsigned short, sp[(long)n * NTOK]);
;       const unsigned o = (bits & 0x8000u) ? (~bits & 0xffffu) : (bits | 0x8000u);
;       Gk[e] = (o << 16) | (unsigned)(127 - n);
;     }
;     SORT16(Gk)
;     MERGE16(R, Gk)
;   }
; }
.LBB0_1186:
	s_waitcnt vmcnt(0)
	ds_write_b128 v100, v[90:93]
	ds_write_b128 v100, v[94:97] offset:1024
	s_waitcnt lgkmcnt(0)
	global_load_dwordx4 v[90:93], v86, s[36:37]
	v_add_u32_e32 v87, 0x80000, v86
	global_load_dwordx4 v[94:97], v87, s[36:37]
	v_add_u32_e32 v86, 0x100000, v86
	ds_read_u16 v22, v101
	ds_read_u16 v61, v101 offset:128
	ds_read_u16 v60, v101 offset:256
	ds_read_u16 v59, v101 offset:384
	ds_read_u16 v58, v101 offset:512
	ds_read_u16 v57, v101 offset:640
	ds_read_u16 v15, v101 offset:768
	ds_read_u16 v14, v101 offset:896
	ds_read_u16 v12, v101 offset:1024
	ds_read_u16 v11, v101 offset:1152
	ds_read_u16 v10, v101 offset:1280
	ds_read_u16 v9, v101 offset:1408
	ds_read_u16 v8, v101 offset:1536
	ds_read_u16 v7, v101 offset:1664
	ds_read_u16 v6, v101 offset:1792
	ds_read_u16 v13, v101 offset:1920
	s_waitcnt lgkmcnt(0)
	v_and_b32_e32 v16, 0xffff, v22
	v_bitop3_b32 v17, v16, s57, v16 bitop3:0xc
	v_or_b32_e32 v16, 0x8000, v16
	v_cmp_gt_i16_e32 vcc, 0, v22
	v_and_b32_e32 v18, 0xffff, v61
	v_and_b32_e32 v19, 0xffff, v60
	v_and_b32_e32 v20, 0xffff, v59
	v_and_b32_e32 v21, 0xffff, v58
	v_and_b32_e32 v62, 0xffff, v57
	v_and_b32_e32 v63, 0xffff, v15
	v_and_b32_e32 v64, 0xffff, v14
	v_and_b32_e32 v65, 0xffff, v12
	v_and_b32_e32 v66, 0xffff, v11
	v_and_b32_e32 v67, 0xffff, v10
	v_and_b32_e32 v68, 0xffff, v9
	v_and_b32_e32 v69, 0xffff, v8
	v_and_b32_e32 v70, 0xffff, v7
	v_and_b32_e32 v71, 0xffff, v6
	v_and_b32_e32 v72, 0xffff, v13
	v_cndmask_b32_e32 v16, v16, v17, vcc
	v_bitop3_b32 v17, v18, s57, v18 bitop3:0xc
	v_or_b32_e32 v18, 0x8000, v18
	v_cmp_gt_i16_e32 vcc, 0, v61
	v_bitop3_b32 v22, v19, s57, v19 bitop3:0xc
	v_or_b32_e32 v19, 0x8000, v19
	v_cmp_gt_i16_e64 s[0:1], 0, v60
	v_bitop3_b32 v60, v20, s57, v20 bitop3:0xc
	v_or_b32_e32 v20, 0x8000, v20
	v_cmp_gt_i16_e64 s[6:7], 0, v59
	v_bitop3_b32 v59, v21, s57, v21 bitop3:0xc
	v_or_b32_e32 v21, 0x8000, v21
	v_cmp_gt_i16_e64 s[8:9], 0, v58
	v_bitop3_b32 v58, v62, s57, v62 bitop3:0xc
	v_or_b32_e32 v61, 0x8000, v62
	v_cmp_gt_i16_e64 s[10:11], 0, v57
	v_bitop3_b32 v57, v63, s57, v63 bitop3:0xc
	v_or_b32_e32 v62, 0x8000, v63
	v_cmp_gt_i16_e64 s[12:13], 0, v15
	v_bitop3_b32 v15, v64, s57, v64 bitop3:0xc
	v_or_b32_e32 v63, 0x8000, v64
	v_cmp_gt_i16_e64 s[14:15], 0, v14
	v_bitop3_b32 v14, v65, s57, v65 bitop3:0xc
	v_or_b32_e32 v64, 0x8000, v65
	v_cmp_gt_i16_e64 s[16:17], 0, v12
	v_bitop3_b32 v12, v66, s57, v66 bitop3:0xc
	v_or_b32_e32 v65, 0x8000, v66
	v_cmp_gt_i16_e64 s[18:19], 0, v11
	v_bitop3_b32 v11, v67, s57, v67 bitop3:0xc
	v_or_b32_e32 v66, 0x8000, v67
	v_cmp_gt_i16_e64 s[20:21], 0, v10
	v_bitop3_b32 v10, v68, s57, v68 bitop3:0xc
	v_or_b32_e32 v67, 0x8000, v68
	v_cmp_gt_i16_e64 s[24:25], 0, v9
	v_bitop3_b32 v9, v69, s57, v69 bitop3:0xc
	v_or_b32_e32 v68, 0x8000, v69
	v_cmp_gt_i16_e64 s[26:27], 0, v8
	v_bitop3_b32 v8, v70, s57, v70 bitop3:0xc
	v_or_b32_e32 v69, 0x8000, v70
	v_cmp_gt_i16_e64 s[28:29], 0, v7
	v_bitop3_b32 v7, v71, s57, v71 bitop3:0xc
	v_or_b32_e32 v70, 0x8000, v71
	v_cmp_gt_i16_e64 s[30:31], 0, v6
	v_bitop3_b32 v6, v72, s57, v72 bitop3:0xc
	v_or_b32_e32 v71, 0x8000, v72
	v_cmp_gt_i16_e64 s[34:35], 0, v13
	v_lshlrev_b32_e32 v13, 16, v16
	v_cndmask_b32_e32 v16, v18, v17, vcc
	v_cndmask_b32_e64 v17, v19, v22, s[0:1]
	v_cndmask_b32_e64 v18, v20, v60, s[6:7]
	v_cndmask_b32_e64 v19, v21, v59, s[8:9]
	v_cndmask_b32_e64 v20, v61, v58, s[10:11]
	v_cndmask_b32_e64 v21, v62, v57, s[12:13]
	v_cndmask_b32_e64 v15, v63, v15, s[14:15]
	v_cndmask_b32_e64 v14, v64, v14, s[16:17]
	v_cndmask_b32_e64 v12, v65, v12, s[18:19]
	v_cndmask_b32_e64 v11, v66, v11, s[20:21]
	v_cndmask_b32_e64 v10, v67, v10, s[24:25]
	v_cndmask_b32_e64 v9, v68, v9, s[26:27]
	v_cndmask_b32_e64 v8, v69, v8, s[28:29]
	v_cndmask_b32_e64 v7, v70, v7, s[30:31]
	v_cndmask_b32_e64 v6, v71, v6, s[34:35]
	v_lshlrev_b32_e32 v16, 16, v16
	v_lshlrev_b32_e32 v17, 16, v17
	v_lshlrev_b32_e32 v18, 16, v18
	v_lshlrev_b32_e32 v19, 16, v19
	v_lshlrev_b32_e32 v20, 16, v20
	v_lshlrev_b32_e32 v21, 16, v21
	v_lshlrev_b32_e32 v15, 16, v15
	v_lshlrev_b32_e32 v14, 16, v14
	v_lshlrev_b32_e32 v12, 16, v12
	v_lshlrev_b32_e32 v11, 16, v11
	v_lshlrev_b32_e32 v10, 16, v10
	v_lshlrev_b32_e32 v9, 16, v9
	v_lshlrev_b32_e32 v8, 16, v8
	v_lshlrev_b32_e32 v7, 16, v7
	v_add3_u32 v13, s91, v13, 15
	v_lshl_add_u32 v6, v6, 16, s91
	v_add3_u32 v16, s91, v16, 14
	v_add3_u32 v17, s91, v17, 13
	v_add3_u32 v18, s91, v18, 12
	v_add3_u32 v19, s91, v19, 11
	v_add3_u32 v20, s91, v20, 10
	v_add3_u32 v21, s91, v21, 9
	v_add3_u32 v15, s91, v15, 8
	v_add3_u32 v14, s91, v14, 7
	v_add3_u32 v12, s91, v12, 6
	v_add3_u32 v11, s91, v11, 5
	v_add3_u32 v10, s91, v10, 4
	v_add3_u32 v9, s91, v9, 3
	v_add3_u32 v8, s91, v8, 2
	v_add3_u32 v7, s91, v7, 1
	v_max_u32_e32 v22, v13, v16
	v_min_u32_e32 v13, v13, v16
	v_max_u32_e32 v16, v17, v18
	v_min_u32_e32 v17, v17, v18
	v_max_u32_e32 v18, v19, v20
	v_min_u32_e32 v19, v19, v20
	v_max_u32_e32 v20, v21, v15
	v_min_u32_e32 v15, v21, v15
	v_max_u32_e32 v21, v14, v12
	v_min_u32_e32 v12, v14, v12
	v_max_u32_e32 v14, v11, v10
	v_min_u32_e32 v10, v11, v10
	v_max_u32_e32 v11, v9, v8
	v_min_u32_e32 v8, v9, v8
	v_max_u32_e32 v9, v7, v6
	v_min_u32_e32 v6, v7, v6
	v_max_u32_e32 v7, v22, v16
	v_min_u32_e32 v16, v22, v16
	v_max_u32_e32 v22, v13, v17
	v_min_u32_e32 v13, v13, v17
	v_max_u32_e32 v17, v18, v20
	v_min_u32_e32 v18, v18, v20
	v_max_u32_e32 v20, v19, v15
	v_min_u32_e32 v15, v19, v15
	v_max_u32_e32 v19, v21, v14
	v_min_u32_e32 v14, v21, v14
	v_max_u32_e32 v21, v12, v10
	v_min_u32_e32 v10, v12, v10
	v_max_u32_e32 v12, v11, v9
	v_min_u32_e32 v9, v11, v9
	v_max_u32_e32 v11, v8, v6
	v_min_u32_e32 v6, v8, v6
	v_max_u32_e32 v8, v22, v16
; DI void topk_half(const _Float16* __restrict__ sp, unsigned (&R)[16]) {
; #pragma unroll
;   for (int e = 0; e < 16; ++e) R[e] = 0u;
; #pragma unroll 1
;   for (int gi = 0; gi < 8; ++gi) {
;     unsigned Gk[16];
; #pragma unroll
;     for (int e = 0; e < 16; ++e) {
;       const int n = gi * 16 + e;
;       const unsigned bits = __builtin_bit_cast(unsigned short, sp[(long)n * NTOK]);
;       const unsigned o = (bits & 0x8000u) ? (~bits & 0xffffu) : (bits | 0x8000u);
;       Gk[e] = (o << 16) | (unsigned)(127 - n);
;     }
;     SORT16(Gk)
;     MERGE16(R, Gk)
	v_min_u32_e32 v16, v22, v16
	v_max_u32_e32 v22, v20, v18
	v_min_u32_e32 v18, v20, v18
	v_max_u32_e32 v20, v21, v14
	v_min_u32_e32 v14, v21, v14
	v_max_u32_e32 v21, v11, v9
	v_min_u32_e32 v9, v11, v9
	v_max_u32_e32 v11, v7, v17
	v_min_u32_e32 v7, v7, v17
	v_max_u32_e32 v17, v13, v15
	v_min_u32_e32 v13, v13, v15
	v_max_u32_e32 v15, v19, v12
	v_min_u32_e32 v12, v19, v12
	v_max_u32_e32 v19, v10, v6
	v_min_u32_e32 v6, v10, v6
	v_max_u32_e32 v10, v8, v22
	v_min_u32_e32 v8, v8, v22
	v_max_u32_e32 v22, v16, v18
	v_min_u32_e32 v16, v16, v18
	v_max_u32_e32 v18, v20, v21
	v_min_u32_e32 v20, v20, v21
	v_max_u32_e32 v21, v14, v9
	v_min_u32_e32 v9, v14, v9
	v_min_u32_e32 v14, v11, v15
	v_max_u32_e32 v57, v13, v6
	v_min_u32_e32 v6, v13, v6
	v_max3_u32 v11, v56, v11, v15
	v_max_u32_e32 v13, v22, v7
	v_min_u32_e32 v7, v22, v7
	v_max_u32_e32 v15, v17, v8
	v_min_u32_e32 v8, v17, v8
	v_max_u32_e32 v17, v21, v12
	v_min_u32_e32 v12, v21, v12
	v_max_u32_e32 v21, v19, v20
	v_min_u32_e32 v19, v19, v20
	v_max_u32_e32 v20, v10, v13
	v_min_u32_e32 v10, v10, v13
	v_max_u32_e32 v13, v15, v7
	v_min_u32_e32 v7, v15, v7
	v_max_u32_e32 v15, v8, v16
	v_min_u32_e32 v8, v8, v16
	v_max_u32_e32 v16, v18, v17
	v_min_u32_e32 v17, v18, v17
	v_max_u32_e32 v18, v21, v12
	v_min_u32_e32 v12, v21, v12
	v_max_u32_e32 v21, v19, v9
	v_min_u32_e32 v9, v19, v9
	v_max_u32_e32 v19, v20, v16
	v_min_u32_e32 v16, v20, v16
	v_max_u32_e32 v20, v10, v17
	v_min_u32_e32 v10, v10, v17
	v_max_u32_e32 v17, v13, v18
	v_min_u32_e32 v13, v13, v18
	v_max_u32_e32 v18, v7, v12
	v_min_u32_e32 v7, v7, v12
	v_max_u32_e32 v12, v15, v21
	v_min_u32_e32 v15, v15, v21
	v_max_u32_e32 v21, v8, v9
	v_min_u32_e32 v8, v8, v9
	v_max_u32_e32 v9, v18, v14
	v_min_u32_e32 v14, v18, v14
	v_max_u32_e32 v18, v12, v16
	v_min_u32_e32 v12, v12, v16
	v_max_u32_e32 v16, v21, v10
	v_min_u32_e32 v10, v21, v10
	v_max_u32_e32 v21, v57, v13
	v_min_u32_e32 v13, v57, v13
	v_max_u32_e32 v22, v20, v9
	v_min_u32_e32 v9, v20, v9
	v_max_u32_e32 v20, v17, v18
	v_min_u32_e32 v17, v17, v18
	v_max_u32_e32 v18, v16, v14
	v_min_u32_e32 v14, v16, v14
	v_max_u32_e32 v16, v21, v12
	v_min_u32_e32 v12, v21, v12
	v_max_u32_e32 v21, v10, v7
	v_min_u32_e32 v7, v10, v7
	v_max_u32_e32 v10, v13, v15
	v_min_u32_e32 v13, v13, v15
	v_max_u32_e32 v6, v55, v6
	v_min_u32_e32 v15, v19, v22
	v_min_u32_e32 v55, v20, v9
	v_min_u32_e32 v56, v17, v18
	v_min_u32_e32 v57, v16, v14
	v_min_u32_e32 v58, v12, v21
	v_min_u32_e32 v59, v10, v7
	v_min_u32_e32 v60, v13, v8
	v_max3_u32 v8, v54, v13, v8
	v_max3_u32 v7, v52, v10, v7
	v_max3_u32 v10, v53, v12, v21
	v_max3_u32 v12, v50, v16, v14
	v_max3_u32 v13, v51, v17, v18
	v_max3_u32 v9, v47, v20, v9
	v_max3_u32 v14, v48, v19, v22
	v_max_u32_e32 v16, v49, v60
	v_max_u32_e32 v17, v46, v59
	v_max_u32_e32 v18, v45, v58
	v_max_u32_e32 v19, v44, v57
	v_max_u32_e32 v20, v43, v56
	v_max_u32_e32 v21, v42, v55
	v_max_u32_e32 v15, v23, v15
	v_max_u32_e32 v22, v6, v12
	v_min_u32_e32 v6, v6, v12
	v_max_u32_e32 v12, v8, v13
	v_min_u32_e32 v8, v8, v13
	v_max_u32_e32 v13, v7, v9
	v_min_u32_e32 v7, v7, v9
	v_max_u32_e32 v9, v10, v14
	v_min_u32_e32 v10, v10, v14
	v_max_u32_e32 v14, v16, v20
	v_min_u32_e32 v16, v16, v20
	v_max_u32_e32 v20, v17, v21
	v_min_u32_e32 v17, v17, v21
	v_max_u32_e32 v21, v18, v15
	v_min_u32_e32 v15, v18, v15
	v_max_u32_e32 v18, v19, v11
	v_min_u32_e32 v11, v19, v11
	v_max_u32_e32 v19, v22, v13
	v_min_u32_e32 v13, v22, v13
	v_max_u32_e32 v22, v12, v9
	v_min_u32_e32 v9, v12, v9
	v_max_u32_e32 v12, v6, v7
	v_min_u32_e32 v6, v6, v7
	v_max_u32_e32 v7, v8, v10
	v_min_u32_e32 v8, v8, v10
	v_max_u32_e32 v10, v14, v21
	v_min_u32_e32 v14, v14, v21
	v_max_u32_e32 v21, v20, v18
	v_min_u32_e32 v18, v20, v18
	v_max_u32_e32 v20, v16, v15
	v_min_u32_e32 v15, v16, v15
	v_max_u32_e32 v16, v17, v11
	v_min_u32_e32 v11, v17, v11
	s_add_i32 s91, s91, -16
	v_max_u32_e32 v17, v19, v22
	v_min_u32_e32 v19, v19, v22
	v_max_u32_e32 v22, v13, v9
	v_min_u32_e32 v9, v13, v9
	v_max_u32_e32 v13, v12, v7
	v_min_u32_e32 v7, v12, v7
	v_max_u32_e32 v12, v6, v8
	v_min_u32_e32 v6, v6, v8
	v_max_u32_e32 v8, v10, v21
	v_min_u32_e32 v10, v10, v21
	v_max_u32_e32 v21, v14, v18
	v_min_u32_e32 v14, v14, v18
	v_max_u32_e32 v18, v20, v16
	v_min_u32_e32 v16, v20, v16
	v_max_u32_e32 v20, v15, v11
	v_min_u32_e32 v11, v15, v11
	s_cmp_lg_u32 s91, -16
	v_max_u32_e32 v55, v17, v8
	v_min_u32_e32 v49, v17, v8
	v_max_u32_e32 v54, v19, v10
	v_min_u32_e32 v46, v19, v10
	v_max_u32_e32 v52, v22, v21
	v_min_u32_e32 v45, v22, v21
	v_max_u32_e32 v53, v9, v14
	v_min_u32_e32 v44, v9, v14
	v_max_u32_e32 v50, v13, v18
	v_min_u32_e32 v43, v13, v18
	v_max_u32_e32 v51, v7, v16
	v_min_u32_e32 v42, v7, v16
	v_max_u32_e32 v47, v12, v20
	v_min_u32_e32 v23, v12, v20
	v_max_u32_e32 v48, v6, v11
	v_min_u32_e32 v56, v6, v11
	s_cbranch_scc1 .LBB0_1186
; DI float key_val16(unsigned k) { const unsigned o = k >> 16; const unsigned short b = (unsigned short)((o & 0x8000u) ? (o & 0x7fffu) : (~o & 0xffffu)); return (float)__builtin_bit_cast(_Float16, b); }
; DI unsigned candkey(float s, int pos) { const unsigned b = __float_as_uint(s); const unsigned o = (b >> 31) ? ~b : (b ^ 0x80000000u); return (o & 0xffffff00u) | (unsigned)(255 - pos); }
; DI void phase10(const Params& P, char* smem) {
;   char* ws = P.ws;
;   const _Float16* ST = (const _Float16*)(ws + OFF_ST);
;   int* Eidx = (int*)(ws + OFF_EIDX); float* G = (float*)(ws + OFF_G);
;   for (long id = (long)VB * 256 + VT; id < (long)NTOK * 8; id += (long)NVB * 256) {
;     const int t = (int)(id & (NTOK - 1)), h = (int)(id >> 15);
;     unsigned R1[16], R2[16];
;     topk_half(ST + ((long)(h * 2 + 0) * 128) * NTOK + t, R1);
;     topk_half(ST + ((long)(h * 2 + 1) * 128) * NTOK + t, R2);
;     float v1[16], v2[16]; unsigned W1[4] = {0u, 0u, 0u, 0u}, W2[4] = {0u, 0u, 0u, 0u};
; #pragma unroll
;     for (int k = 0; k < 16; ++k) {
;       v1[k] = key_val16(R1[k]); v2[k] = key_val16(R2[k]);
;       W1[k >> 2] |= (127u - (R1[k] & 127u)) << ((k & 3) * 8);
;       W2[k >> 2] |= (127u - (R2[k] & 127u)) << ((k & 3) * 8);
;     }
;     unsigned C0[16], C1[16], C2[16], C3[16];
	v_lshlrev_b32_e32 v5, 8, v24
	v_lshlrev_b32_e32 v6, 16, v40
	v_and_b32_e32 v4, 0x7f, v35
	v_and_b32_e32 v5, 0x7f00, v5
	v_and_b32_e32 v6, 0x7f0000, v6
	v_or3_b32 v4, v5, v4, v6
	v_and_b32_sdwa v5, v46, s57 dst_sel:DWORD dst_unused:UNUSED_PAD src0_sel:WORD_1 src1_sel:DWORD
	v_xor_b32_sdwa v7, v46, v27 dst_sel:DWORD dst_unused:UNUSED_PAD src0_sel:WORD_1 src1_sel:DWORD
	v_cmp_gt_i32_e32 vcc, 0, v46
	v_and_b32_sdwa v6, v41, s57 dst_sel:DWORD dst_unused:UNUSED_PAD src0_sel:WORD_1 src1_sel:DWORD
	v_xor_b32_sdwa v8, v41, v27 dst_sel:DWORD dst_unused:UNUSED_PAD src0_sel:WORD_1 src1_sel:DWORD
	v_cndmask_b32_e32 v5, v7, v5, vcc
	v_cmp_gt_i32_e32 vcc, 0, v41
	v_xor_b32_sdwa v7, v39, v27 dst_sel:DWORD dst_unused:UNUSED_PAD src0_sel:WORD_1 src1_sel:DWORD
	v_xor_b32_sdwa v11, v36, v27 dst_sel:DWORD dst_unused:UNUSED_PAD src0_sel:WORD_1 src1_sel:DWORD
	v_cndmask_b32_e32 v6, v8, v6, vcc
	v_cvt_f32_f16_e32 v8, v5
	v_lshlrev_b32_e32 v5, 24, v41
	v_and_b32_e32 v5, 0x7f000000, v5
	v_cvt_f32_f16_e32 v12, v6
	v_bitop3_b32 v15, v4, s75, v5 bitop3:0x36
	v_and_b32_sdwa v4, v54, s57 dst_sel:DWORD dst_unused:UNUSED_PAD src0_sel:WORD_1 src1_sel:DWORD
	v_xor_b32_sdwa v6, v54, v27 dst_sel:DWORD dst_unused:UNUSED_PAD src0_sel:WORD_1 src1_sel:DWORD
	v_cmp_gt_i32_e32 vcc, 0, v54
	v_and_b32_sdwa v5, v39, s57 dst_sel:DWORD dst_unused:UNUSED_PAD src0_sel:WORD_1 src1_sel:DWORD
	v_xor_b32_sdwa v13, v24, v27 dst_sel:DWORD dst_unused:UNUSED_PAD src0_sel:WORD_1 src1_sel:DWORD
	v_cndmask_b32_e32 v4, v6, v4, vcc
	v_cmp_gt_i32_e32 vcc, 0, v39
	v_cvt_f32_f16_e32 v9, v4
	v_and_b32_sdwa v4, v52, s57 dst_sel:DWORD dst_unused:UNUSED_PAD src0_sel:WORD_1 src1_sel:DWORD
	v_cndmask_b32_e32 v5, v7, v5, vcc
	v_xor_b32_sdwa v6, v52, v27 dst_sel:DWORD dst_unused:UNUSED_PAD src0_sel:WORD_1 src1_sel:DWORD
	v_cmp_gt_i32_e32 vcc, 0, v52
	v_cvt_f32_f16_e32 v10, v5
	v_and_b32_sdwa v5, v40, s57 dst_sel:DWORD dst_unused:UNUSED_PAD src0_sel:WORD_1 src1_sel:DWORD
	v_xor_b32_sdwa v7, v40, v27 dst_sel:DWORD dst_unused:UNUSED_PAD src0_sel:WORD_1 src1_sel:DWORD
	v_cndmask_b32_e32 v4, v6, v4, vcc
	v_cmp_gt_i32_e32 vcc, 0, v40
	v_not_b32_sdwa v6, v25 dst_sel:DWORD dst_unused:UNUSED_PAD src0_sel:WORD_1
	v_cvt_f32_f16_e32 v21, v4
	v_cndmask_b32_e32 v5, v7, v5, vcc
	v_cvt_f32_f16_e32 v22, v5
	v_bfe_u32 v5, v25, 16, 15
	v_cmp_gt_i32_e32 vcc, 0, v25
	v_not_b32_sdwa v7, v38 dst_sel:DWORD dst_unused:UNUSED_PAD src0_sel:WORD_1
	v_and_b32_e32 v4, 0x7f, v39
	v_cndmask_b32_e32 v5, v6, v5, vcc
	v_cvt_f32_f16_e32 v14, v5
	v_bfe_u32 v5, v45, 16, 15
	v_not_b32_sdwa v6, v45 dst_sel:DWORD dst_unused:UNUSED_PAD src0_sel:WORD_1
	v_cmp_gt_i32_e32 vcc, 0, v45
	s_movk_i32 s0, 0xfe
	v_xor_b32_sdwa v57, v50, v27 dst_sel:DWORD dst_unused:UNUSED_PAD src0_sel:WORD_1 src1_sel:DWORD
	v_cndmask_b32_e32 v5, v6, v5, vcc
	v_bfe_u32 v6, v38, 16, 15
	v_cmp_gt_i32_e32 vcc, 0, v38
	v_cvt_f32_f16_e32 v20, v5
	v_lshlrev_b32_e32 v5, 8, v25
	v_cndmask_b32_e32 v6, v7, v6, vcc
	v_cvt_f32_f16_e32 v16, v6
	v_bfe_u32 v6, v53, 16, 15
	v_not_b32_sdwa v7, v53 dst_sel:DWORD dst_unused:UNUSED_PAD src0_sel:WORD_1
	v_cmp_gt_i32_e32 vcc, 0, v53
	v_and_b32_e32 v5, 0x7f00, v5
	v_xor_b32_sdwa v81, v32, v27 dst_sel:DWORD dst_unused:UNUSED_PAD src0_sel:WORD_1 src1_sel:DWORD
	v_cndmask_b32_e32 v6, v7, v6, vcc
	v_cvt_f32_f16_e32 v25, v6
	v_lshlrev_b32_e32 v6, 16, v38
	v_and_b32_e32 v6, 0x7f0000, v6
	v_or3_b32 v4, v5, v4, v6
	v_and_b32_sdwa v5, v49, s57 dst_sel:DWORD dst_unused:UNUSED_PAD src0_sel:WORD_1 src1_sel:DWORD
	v_xor_b32_sdwa v7, v49, v27 dst_sel:DWORD dst_unused:UNUSED_PAD src0_sel:WORD_1 src1_sel:DWORD
	v_cmp_gt_i32_e32 vcc, 0, v49
	v_and_b32_sdwa v6, v36, s57 dst_sel:DWORD dst_unused:UNUSED_PAD src0_sel:WORD_1 src1_sel:DWORD
	v_xor_b32_sdwa v38, v35, v27 dst_sel:DWORD dst_unused:UNUSED_PAD src0_sel:WORD_1 src1_sel:DWORD
	v_cndmask_b32_e32 v5, v7, v5, vcc
	v_cmp_gt_i32_e32 vcc, 0, v36
	s_nop 1
	v_cndmask_b32_e32 v7, v11, v6, vcc
	v_cvt_f32_f16_e32 v18, v7
	v_and_b32_sdwa v7, v24, s57 dst_sel:DWORD dst_unused:UNUSED_PAD src0_sel:WORD_1 src1_sel:DWORD
	v_cmp_gt_i32_e32 vcc, 0, v24
	v_cvt_f32_f16_e32 v6, v5
	v_and_b32_sdwa v5, v44, s57 dst_sel:DWORD dst_unused:UNUSED_PAD src0_sel:WORD_1 src1_sel:DWORD
	v_xor_b32_sdwa v11, v44, v27 dst_sel:DWORD dst_unused:UNUSED_PAD src0_sel:WORD_1 src1_sel:DWORD
	v_cndmask_b32_e32 v7, v13, v7, vcc
	v_cmp_gt_i32_e32 vcc, 0, v44
	v_cvt_f32_f16_e32 v64, v7
	v_lshlrev_b32_e32 v7, 16, v31
	v_cndmask_b32_e32 v5, v11, v5, vcc
	v_cvt_f32_f16_e32 v24, v5
	v_lshlrev_b32_e32 v5, 24, v36
	v_and_b32_e32 v5, 0x7f000000, v5
	v_bitop3_b32 v17, v4, s75, v5 bitop3:0x36
	v_lshlrev_b32_e32 v5, 8, v32
	v_and_b32_e32 v4, 0x7f, v33
	v_and_b32_e32 v5, 0x7f00, v5
	v_and_b32_e32 v7, 0x7f0000, v7
	v_or3_b32 v4, v5, v4, v7
	v_lshlrev_b32_e32 v5, 24, v30
	v_and_b32_e32 v5, 0x7f000000, v5
	v_bitop3_b32 v19, v4, s75, v5 bitop3:0x36
	v_lshlrev_b32_e32 v5, 8, v1
	v_and_b32_e32 v11, 0x7f00, v5
	v_and_b32_sdwa v5, v55, s57 dst_sel:DWORD dst_unused:UNUSED_PAD src0_sel:WORD_1 src1_sel:DWORD
	v_xor_b32_sdwa v13, v55, v27 dst_sel:DWORD dst_unused:UNUSED_PAD src0_sel:WORD_1 src1_sel:DWORD
	v_cmp_gt_i32_e32 vcc, 0, v55
	v_and_b32_sdwa v7, v34, s57 dst_sel:DWORD dst_unused:UNUSED_PAD src0_sel:WORD_1 src1_sel:DWORD
	v_xor_b32_sdwa v36, v34, v27 dst_sel:DWORD dst_unused:UNUSED_PAD src0_sel:WORD_1 src1_sel:DWORD
	v_cndmask_b32_e32 v5, v13, v5, vcc
	v_cmp_gt_i32_e32 vcc, 0, v34
	v_and_b32_e32 v4, 0x7f, v3
	s_nop 0
	v_cndmask_b32_e32 v13, v36, v7, vcc
	v_cvt_f32_f16_e32 v7, v5
	v_cvt_f32_f16_e32 v5, v13
	v_bfe_u32 v13, v48, 16, 15
	v_not_b32_sdwa v36, v48 dst_sel:DWORD dst_unused:UNUSED_PAD src0_sel:WORD_1
	v_cmp_gt_i32_e32 vcc, 0, v48
	s_nop 1
	v_cndmask_b32_e32 v13, v36, v13, vcc
; DI unsigned candkey(float s, int pos) { const unsigned b = __float_as_uint(s); const unsigned o = (b >> 31) ? ~b : (b ^ 0x80000000u); return (o & 0xffffff00u) | (unsigned)(255 - pos); }
; DI void phase10(const Params& P, char* smem) {
;     ...
;     C0[0] = candkey(v1[0] + v2[0], 0);
;     C0[1] = candkey(v1[0] + v2[1], 1);
;     C0[2] = candkey(v1[0] + v2[2], 2);
;     C0[3] = candkey(v1[0] + v2[3], 3);
;     C0[4] = candkey(v1[0] + v2[4], 4);
;     C0[5] = candkey(v1[0] + v2[5], 5);
;     C0[6] = candkey(v1[0] + v2[6], 6);
;     C0[7] = candkey(v1[0] + v2[7], 7);
;     C0[8] = candkey(v1[0] + v2[8], 8);
;     C0[9] = candkey(v1[0] + v2[9], 9);
;     C0[10] = candkey(v1[0] + v2[10], 10);
;     C0[11] = candkey(v1[0] + v2[11], 11);
;     C0[12] = candkey(v1[0] + v2[12], 12);
;     C0[13] = candkey(v1[0] + v2[13], 13);
;     C0[14] = candkey(v1[0] + v2[14], 14);
;     C0[15] = candkey(v1[0] + v2[15], 15);
;     C1[0] = candkey(v1[1] + v2[0], 16);
;     C1[1] = candkey(v1[1] + v2[1], 17);
;     C1[2] = candkey(v1[1] + v2[2], 18);
;     C1[3] = candkey(v1[1] + v2[3], 19);
;     C1[4] = candkey(v1[1] + v2[4], 20);
;     C1[5] = candkey(v1[1] + v2[5], 21);
;     C1[6] = candkey(v1[1] + v2[6], 22);
;     C1[7] = candkey(v1[1] + v2[7], 23);
;     C1[8] = candkey(v1[2] + v2[0], 32);
;     C1[9] = candkey(v1[2] + v2[1], 33);
;     C1[10] = candkey(v1[2] + v2[2], 34);
;     C1[11] = candkey(v1[2] + v2[3], 35);
;     C1[12] = candkey(v1[2] + v2[4], 36);
;     C1[13] = candkey(v1[3] + v2[0], 48);
;     C1[14] = candkey(v1[3] + v2[1], 49);
;     C1[15] = candkey(v1[3] + v2[2], 50);
	v_cvt_f32_f16_e32 v67, v13
	v_lshlrev_b32_e32 v13, 16, v34
	v_and_b32_e32 v13, 0x7f0000, v13
	v_or3_b32 v11, v11, v4, v13
	v_bfe_u32 v4, v37, 16, 15
	v_not_b32_sdwa v13, v37 dst_sel:DWORD dst_unused:UNUSED_PAD src0_sel:WORD_1
	v_cmp_gt_i32_e32 vcc, 0, v37
	v_xor_b32_sdwa v36, v56, v27 dst_sel:DWORD dst_unused:UNUSED_PAD src0_sel:WORD_1 src1_sel:DWORD
	v_and_b32_sdwa v34, v35, s57 dst_sel:DWORD dst_unused:UNUSED_PAD src0_sel:WORD_1 src1_sel:DWORD
	v_cndmask_b32_e32 v4, v13, v4, vcc
	v_and_b32_sdwa v13, v56, s57 dst_sel:DWORD dst_unused:UNUSED_PAD src0_sel:WORD_1 src1_sel:DWORD
	v_cmp_gt_i32_e32 vcc, 0, v56
	v_cvt_f32_f16_e32 v4, v4
	s_nop 0
	v_cndmask_b32_e32 v13, v36, v13, vcc
	v_cmp_gt_i32_e32 vcc, 0, v35
	v_cvt_f32_f16_e32 v66, v13
	v_lshlrev_b32_e32 v13, 24, v37
	v_cndmask_b32_e32 v34, v38, v34, vcc
	v_cvt_f32_f16_e32 v68, v34
	v_and_b32_e32 v13, 0x7f000000, v13
	v_bitop3_b32 v34, v11, s75, v13 bitop3:0x36
	v_pk_add_f32 v[36:37], v[68:69], v[6:7] op_sel_hi:[0,1]
	v_cmp_lt_i32_e32 vcc, -1, v37
	v_pk_add_f32 v[38:39], v[68:69], v[8:9] op_sel_hi:[0,1]
	v_and_b32_e32 v13, 0xffffff00, v36
	v_cndmask_b32_e32 v11, v28, v29, vcc
	v_cmp_lt_i32_e32 vcc, -1, v36
	v_bitop3_b32 v35, v11, s3, v37 bitop3:0xde
	v_pk_add_f32 v[40:41], v[68:69], v[20:21] op_sel_hi:[0,1]
	v_cndmask_b32_e32 v11, v28, v29, vcc
	v_cmp_lt_i32_e32 vcc, -1, v39
	v_bitop3_b32 v36, v11, s0, v13 bitop3:0xde
	v_and_b32_e32 v13, 0xffffff00, v39
	v_cndmask_b32_e32 v11, v28, v29, vcc
	s_movk_i32 s0, 0xfd
	v_cmp_lt_i32_e32 vcc, -1, v38
	v_bitop3_b32 v37, v11, s0, v13 bitop3:0xde
	v_and_b32_e32 v13, 0xffffff00, v38
	v_cndmask_b32_e32 v11, v28, v29, vcc
	s_movk_i32 s0, 0xfc
	v_cmp_lt_i32_e32 vcc, -1, v41
	v_bitop3_b32 v38, v11, s0, v13 bitop3:0xde
	v_and_b32_e32 v13, 0xffffff00, v41
	v_cndmask_b32_e32 v11, v28, v29, vcc
	s_movk_i32 s0, 0xfb
	v_cmp_lt_i32_e32 vcc, -1, v40
	v_pk_add_f32 v[58:59], v[68:69], v[24:25] op_sel_hi:[0,1]
	v_bitop3_b32 v39, v11, s0, v13 bitop3:0xde
	v_cndmask_b32_e32 v11, v28, v29, vcc
	v_and_b32_e32 v13, 0xffffff00, v40
	s_movk_i32 s0, 0xfa
	v_cmp_lt_i32_e32 vcc, -1, v59
	v_bitop3_b32 v40, v11, s0, v13 bitop3:0xde
	v_and_b32_e32 v13, 0xffffff00, v59
	v_cndmask_b32_e32 v11, v28, v29, vcc
	s_movk_i32 s0, 0xf9
	v_bitop3_b32 v41, v11, s0, v13 bitop3:0xde
	v_and_b32_sdwa v11, v50, s57 dst_sel:DWORD dst_unused:UNUSED_PAD src0_sel:WORD_1 src1_sel:DWORD
	v_cmp_gt_i32_e32 vcc, 0, v50
	v_and_b32_sdwa v13, v43, s57 dst_sel:DWORD dst_unused:UNUSED_PAD src0_sel:WORD_1 src1_sel:DWORD
	v_xor_b32_sdwa v59, v43, v27 dst_sel:DWORD dst_unused:UNUSED_PAD src0_sel:WORD_1 src1_sel:DWORD
	v_cndmask_b32_e32 v11, v57, v11, vcc
	v_cmp_gt_i32_e32 vcc, 0, v43
	v_cvt_f32_f16_e32 v61, v11
	s_movk_i32 s0, 0xf8
	v_cndmask_b32_e32 v13, v59, v13, vcc
	v_cvt_f32_f16_e32 v60, v13
	v_cmp_lt_i32_e32 vcc, -1, v58
	v_and_b32_e32 v13, 0xffffff00, v58
	v_xor_b32_sdwa v59, v51, v27 dst_sel:DWORD dst_unused:UNUSED_PAD src0_sel:WORD_1 src1_sel:DWORD
	v_pk_add_f32 v[60:61], v[68:69], v[60:61] op_sel_hi:[0,1]
	v_cndmask_b32_e32 v11, v28, v29, vcc
	v_cmp_lt_i32_e32 vcc, -1, v61
	v_bitop3_b32 v57, v11, s0, v13 bitop3:0xde
	v_and_b32_e32 v13, 0xffffff00, v61
	v_cndmask_b32_e32 v11, v28, v29, vcc
	s_movk_i32 s0, 0xf7
	v_bitop3_b32 v58, v11, s0, v13 bitop3:0xde
	v_and_b32_sdwa v11, v51, s57 dst_sel:DWORD dst_unused:UNUSED_PAD src0_sel:WORD_1 src1_sel:DWORD
	v_cmp_gt_i32_e32 vcc, 0, v51
	v_and_b32_sdwa v13, v42, s57 dst_sel:DWORD dst_unused:UNUSED_PAD src0_sel:WORD_1 src1_sel:DWORD
	v_xor_b32_sdwa v61, v42, v27 dst_sel:DWORD dst_unused:UNUSED_PAD src0_sel:WORD_1 src1_sel:DWORD
	v_cndmask_b32_e32 v11, v59, v11, vcc
	v_cmp_gt_i32_e32 vcc, 0, v42
	v_cvt_f32_f16_e32 v63, v11
	s_movk_i32 s0, 0xf6
	v_cndmask_b32_e32 v13, v61, v13, vcc
	v_cvt_f32_f16_e32 v62, v13
	v_cmp_lt_i32_e32 vcc, -1, v60
	v_and_b32_e32 v13, 0xffffff00, v60
	v_xor_b32_sdwa v61, v47, v27 dst_sel:DWORD dst_unused:UNUSED_PAD src0_sel:WORD_1 src1_sel:DWORD
	v_pk_add_f32 v[62:63], v[68:69], v[62:63] op_sel_hi:[0,1]
	v_cndmask_b32_e32 v11, v28, v29, vcc
	v_cmp_lt_i32_e32 vcc, -1, v63
	v_bitop3_b32 v59, v11, s0, v13 bitop3:0xde
	v_and_b32_e32 v13, 0xffffff00, v63
	v_cndmask_b32_e32 v11, v28, v29, vcc
	s_movk_i32 s0, 0xf5
	v_bitop3_b32 v60, v11, s0, v13 bitop3:0xde
	v_and_b32_sdwa v11, v47, s57 dst_sel:DWORD dst_unused:UNUSED_PAD src0_sel:WORD_1 src1_sel:DWORD
	v_cmp_gt_i32_e32 vcc, 0, v47
	v_and_b32_sdwa v13, v23, s57 dst_sel:DWORD dst_unused:UNUSED_PAD src0_sel:WORD_1 src1_sel:DWORD
	v_xor_b32_sdwa v63, v23, v27 dst_sel:DWORD dst_unused:UNUSED_PAD src0_sel:WORD_1 src1_sel:DWORD
	v_cndmask_b32_e32 v11, v61, v11, vcc
	v_cmp_gt_i32_e32 vcc, 0, v23
	v_cvt_f32_f16_e32 v71, v11
	s_movk_i32 s0, 0xf4
	v_cndmask_b32_e32 v13, v63, v13, vcc
	v_cvt_f32_f16_e32 v70, v13
	v_cmp_lt_i32_e32 vcc, -1, v62
	v_and_b32_e32 v13, 0xffffff00, v62
	v_pk_add_f32 v[66:67], v[68:69], v[66:67] op_sel_hi:[0,1]
	v_pk_add_f32 v[70:71], v[68:69], v[70:71] op_sel_hi:[0,1]
	v_cndmask_b32_e32 v11, v28, v29, vcc
	v_cmp_lt_i32_e32 vcc, -1, v71
	v_bitop3_b32 v61, v11, s0, v13 bitop3:0xde
	v_and_b32_e32 v13, 0xffffff00, v71
	v_cndmask_b32_e32 v11, v28, v29, vcc
	s_movk_i32 s0, 0xf3
	v_cmp_lt_i32_e32 vcc, -1, v70
	v_bitop3_b32 v62, v11, s0, v13 bitop3:0xde
	v_and_b32_e32 v13, 0xffffff00, v70
	v_cndmask_b32_e32 v11, v28, v29, vcc
	s_movk_i32 s0, 0xf2
	v_cmp_lt_i32_e32 vcc, -1, v67
	v_bitop3_b32 v63, v11, s0, v13 bitop3:0xde
	v_and_b32_e32 v13, 0xffffff00, v67
	v_cndmask_b32_e32 v11, v28, v29, vcc
	s_movk_i32 s0, 0xf1
	v_bitop3_b32 v65, v11, s0, v13 bitop3:0xde
	v_cmp_lt_i32_e32 vcc, -1, v66
	v_and_b32_e32 v13, 0xffffff00, v66
	v_pk_add_f32 v[66:67], v[64:65], v[6:7] op_sel_hi:[0,1]
; DI unsigned candkey(float s, int pos) { const unsigned b = __float_as_uint(s); const unsigned o = (b >> 31) ? ~b : (b ^ 0x80000000u); return (o & 0xffffff00u) | (unsigned)(255 - pos); }
; DI void phase10(const Params& P, char* smem) {
;     ...
;     C1[0] = candkey(v1[1] + v2[0], 16);
;     C1[1] = candkey(v1[1] + v2[1], 17);
;     C1[2] = candkey(v1[1] + v2[2], 18);
;     C1[3] = candkey(v1[1] + v2[3], 19);
;     C1[4] = candkey(v1[1] + v2[4], 20);
;     C1[5] = candkey(v1[1] + v2[5], 21);
;     C1[6] = candkey(v1[1] + v2[6], 22);
;     C1[7] = candkey(v1[1] + v2[7], 23);
;     C1[8] = candkey(v1[2] + v2[0], 32);
;     C1[9] = candkey(v1[2] + v2[1], 33);
;     C1[10] = candkey(v1[2] + v2[2], 34);
;     C1[11] = candkey(v1[2] + v2[3], 35);
;     C1[12] = candkey(v1[2] + v2[4], 36);
;     C1[13] = candkey(v1[3] + v2[0], 48);
;     C1[14] = candkey(v1[3] + v2[1], 49);
;     C1[15] = candkey(v1[3] + v2[2], 50);
;     C2[0] = candkey(v1[3] + v2[3], 51);
;     C2[1] = candkey(v1[4] + v2[0], 64);
;     C2[2] = candkey(v1[4] + v2[1], 65);
;     C2[3] = candkey(v1[4] + v2[2], 66);
;     C2[4] = candkey(v1[5] + v2[0], 80);
;     C2[5] = candkey(v1[5] + v2[1], 81);
;     C2[6] = candkey(v1[6] + v2[0], 96);
;     C2[7] = candkey(v1[6] + v2[1], 97);
;     C2[8] = candkey(v1[7] + v2[0], 112);
;     C2[9] = candkey(v1[7] + v2[1], 113);
;     C2[10] = candkey(v1[8] + v2[0], 128);
;     C2[11] = candkey(v1[9] + v2[0], 144);
;     C2[12] = candkey(v1[10] + v2[0], 160);
;     C2[13] = candkey(v1[11] + v2[0], 176);
;     C2[14] = candkey(v1[12] + v2[0], 192);
;     C2[15] = candkey(v1[13] + v2[0], 208);
;     C3[0] = candkey(v1[14] + v2[0], 224);
	v_cndmask_b32_e32 v11, v28, v29, vcc
	s_movk_i32 s0, 0xf0
	v_cmp_lt_i32_e32 vcc, -1, v67
	v_bitop3_b32 v68, v11, s0, v13 bitop3:0xde
	v_and_b32_e32 v13, 0xffffff00, v67
	v_cndmask_b32_e32 v11, v28, v29, vcc
	s_movk_i32 s0, 0xef
	v_bitop3_b32 v69, v11, s0, v13 bitop3:0xde
	v_cmp_lt_i32_e32 vcc, -1, v66
	v_and_b32_e32 v13, 0xffffff00, v66
	v_pk_add_f32 v[66:67], v[64:65], v[8:9] op_sel_hi:[0,1]
	v_cndmask_b32_e32 v11, v28, v29, vcc
	s_movk_i32 s0, 0xee
	v_cmp_lt_i32_e32 vcc, -1, v67
	v_bitop3_b32 v70, v11, s0, v13 bitop3:0xde
	v_and_b32_e32 v13, 0xffffff00, v67
	v_cndmask_b32_e32 v11, v28, v29, vcc
	s_movk_i32 s0, 0xed
	v_bitop3_b32 v71, v11, s0, v13 bitop3:0xde
	v_cmp_lt_i32_e32 vcc, -1, v66
	v_and_b32_e32 v13, 0xffffff00, v66
	v_pk_add_f32 v[66:67], v[64:65], v[20:21] op_sel_hi:[0,1]
	v_cndmask_b32_e32 v11, v28, v29, vcc
	s_movk_i32 s0, 0xec
	v_cmp_lt_i32_e32 vcc, -1, v67
	v_bitop3_b32 v72, v11, s0, v13 bitop3:0xde
	v_and_b32_e32 v13, 0xffffff00, v67
	v_cndmask_b32_e32 v11, v28, v29, vcc
	s_movk_i32 s0, 0xeb
	v_cmp_lt_i32_e32 vcc, -1, v66
	v_pk_add_f32 v[24:25], v[64:65], v[24:25] op_sel_hi:[0,1]
	v_bitop3_b32 v67, v11, s0, v13 bitop3:0xde
	v_cndmask_b32_e32 v11, v28, v29, vcc
	v_and_b32_e32 v13, 0xffffff00, v66
	s_movk_i32 s0, 0xea
	v_cmp_lt_i32_e32 vcc, -1, v25
	v_bitop3_b32 v66, v11, s0, v13 bitop3:0xde
	v_and_b32_e32 v13, 0xffffff00, v25
	v_cndmask_b32_e32 v11, v28, v29, vcc
	s_movk_i32 s0, 0xe9
	v_bitop3_b32 v64, v11, s0, v13 bitop3:0xde
	v_cmp_lt_i32_e32 vcc, -1, v24
	v_and_b32_e32 v13, 0xffffff00, v24
	v_pk_add_f32 v[24:25], v[22:23], v[6:7] op_sel_hi:[0,1]
	v_cndmask_b32_e32 v11, v28, v29, vcc
	v_cmp_lt_i32_e32 vcc, -1, v25
	v_bitop3_b32 v73, v11, s92, v13 bitop3:0xde
	v_and_b32_e32 v13, 0xffffff00, v25
	v_cndmask_b32_e32 v11, v28, v29, vcc
	v_bitop3_b32 v74, v11, s93, v13 bitop3:0xde
	v_cmp_lt_i32_e32 vcc, -1, v24
	v_and_b32_e32 v13, 0xffffff00, v24
	v_pk_add_f32 v[24:25], v[22:23], v[8:9] op_sel_hi:[0,1]
	v_cndmask_b32_e32 v11, v28, v29, vcc
	v_cmp_lt_i32_e32 vcc, -1, v25
	v_bitop3_b32 v75, v11, s94, v13 bitop3:0xde
	v_and_b32_e32 v13, 0xffffff00, v25
	v_cndmask_b32_e32 v11, v28, v29, vcc
	v_cmp_lt_i32_e32 vcc, -1, v24
	v_bitop3_b32 v76, v11, s95, v13 bitop3:0xde
	v_and_b32_e32 v13, 0xffffff00, v24
	v_cndmask_b32_e32 v11, v28, v29, vcc
	v_bitop3_b32 v77, v11, s96, v13 bitop3:0xde
	v_mov_b32_e32 v13, v22
	v_mov_b32_e32 v20, v7
	v_pk_add_f32 v[20:21], v[12:13], v[20:21]
	s_movk_i32 s0, 0x7f
	v_cmp_lt_i32_e32 vcc, -1, v21
	v_and_b32_e32 v13, 0xffffff00, v21
	v_mov_b32_e32 v21, v6
	v_cndmask_b32_e32 v11, v28, v29, vcc
	v_bitop3_b32 v22, v11, s97, v13 bitop3:0xde
	v_cmp_lt_i32_e32 vcc, -1, v20
	v_and_b32_e32 v13, 0xffffff00, v20
	v_mov_b32_e32 v20, v9
	v_pk_add_f32 v[24:25], v[12:13], v[20:21] op_sel_hi:[0,1]
	v_cndmask_b32_e32 v11, v28, v29, vcc
	v_cmp_lt_i32_e32 vcc, -1, v25
	v_bitop3_b32 v78, v11, s4, v13 bitop3:0xde
	v_and_b32_e32 v11, 0xffffff00, v25
	v_cndmask_b32_e32 v9, v28, v29, vcc
	v_cmp_lt_i32_e32 vcc, -1, v24
	v_bitop3_b32 v25, v9, s5, v11 bitop3:0xde
	v_and_b32_e32 v11, 0xffffff00, v24
	v_cndmask_b32_e32 v9, v28, v29, vcc
	v_bitop3_b32 v24, v9, s80, v11 bitop3:0xde
	v_mov_b32_e32 v11, v12
	v_mov_b32_e32 v12, v7
	v_mov_b32_e32 v13, v8
	v_pk_add_f32 v[8:9], v[10:11], v[12:13]
	s_nop 0
	v_cmp_lt_i32_e32 vcc, -1, v9
	v_and_b32_e32 v9, 0xffffff00, v9
	s_nop 0
	v_cndmask_b32_e32 v11, v28, v29, vcc
	v_cmp_lt_i32_e32 vcc, -1, v8
	v_bitop3_b32 v12, v11, s81, v9 bitop3:0xde
	v_and_b32_e32 v8, 0xffffff00, v8
	v_cndmask_b32_e32 v9, v28, v29, vcc
	v_bitop3_b32 v13, v9, s22, v8 bitop3:0xde
	v_pk_add_f32 v[8:9], v[10:11], v[20:21] op_sel_hi:[0,1]
	v_cmp_lt_i32_e32 vcc, -1, v9
	v_and_b32_e32 v9, 0xffffff00, v9
	v_xor_b32_sdwa v11, v33, v27 dst_sel:DWORD dst_unused:UNUSED_PAD src0_sel:WORD_1 src1_sel:DWORD
	v_cndmask_b32_e32 v10, v28, v29, vcc
	v_cmp_lt_i32_e32 vcc, -1, v8
	v_bitop3_b32 v20, v10, s23, v9 bitop3:0xde
	v_and_b32_e32 v8, 0xffffff00, v8
	v_cndmask_b32_e32 v9, v28, v29, vcc
	v_bitop3_b32 v21, v9, s82, v8 bitop3:0xde
	v_pk_add_f32 v[8:9], v[14:15], v[6:7] op_sel_hi:[0,1]
	v_cmp_lt_i32_e32 vcc, -1, v9
	v_and_b32_e32 v9, 0xffffff00, v9
	v_max_u32_e32 v84, v12, v13
	v_cndmask_b32_e32 v10, v28, v29, vcc
	v_cmp_lt_i32_e32 vcc, -1, v8
	v_bitop3_b32 v14, v10, s83, v9 bitop3:0xde
	v_and_b32_e32 v8, 0xffffff00, v8
	v_cndmask_b32_e32 v9, v28, v29, vcc
	v_bitop3_b32 v79, v9, s44, v8 bitop3:0xde
	v_pk_add_f32 v[8:9], v[16:17], v[6:7] op_sel_hi:[0,1]
	v_cmp_lt_i32_e32 vcc, -1, v9
	v_and_b32_e32 v9, 0xffffff00, v9
	v_min_u32_e32 v12, v12, v13
	v_cndmask_b32_e32 v10, v28, v29, vcc
	v_cmp_lt_i32_e32 vcc, -1, v8
	v_bitop3_b32 v16, v10, s45, v9 bitop3:0xde
	v_and_b32_e32 v8, 0xffffff00, v8
	v_cndmask_b32_e32 v9, v28, v29, vcc
	v_bitop3_b32 v80, v9, s33, v8 bitop3:0xde
	v_pk_add_f32 v[8:9], v[18:19], v[6:7] op_sel_hi:[0,1]
	v_cmp_lt_i32_e32 vcc, -1, v9
	v_and_b32_e32 v9, 0xffffff00, v9
	v_and_b32_sdwa v10, v32, s57 dst_sel:DWORD dst_unused:UNUSED_PAD src0_sel:WORD_1 src1_sel:DWORD
	v_cndmask_b32_e32 v6, v28, v29, vcc
	v_cmp_lt_i32_e32 vcc, -1, v8
	v_bitop3_b32 v18, v6, s87, v9 bitop3:0xde
	v_and_b32_sdwa v9, v33, s57 dst_sel:DWORD dst_unused:UNUSED_PAD src0_sel:WORD_1 src1_sel:DWORD
	v_cndmask_b32_e32 v6, v28, v29, vcc
	v_cmp_gt_i32_e32 vcc, 0, v33
	v_and_b32_e32 v8, 0xffffff00, v8
	v_xor_b32_sdwa v33, v30, v27 dst_sel:DWORD dst_unused:UNUSED_PAD src0_sel:WORD_1 src1_sel:DWORD
	v_cndmask_b32_e32 v9, v11, v9, vcc
	v_cmp_gt_i32_e32 vcc, 0, v32
	v_cvt_f32_f16_e32 v11, v9
	v_bitop3_b32 v32, v6, s2, v8 bitop3:0xde
	v_cndmask_b32_e32 v10, v81, v10, vcc
	v_cvt_f32_f16_e32 v10, v10
	v_mov_b32_e32 v6, v7
	v_max_u32_e32 v13, v20, v21
	v_min_u32_e32 v20, v20, v21
; DI unsigned candkey(float s, int pos) { const unsigned b = __float_as_uint(s); const unsigned o = (b >> 31) ? ~b : (b ^ 0x80000000u); return (o & 0xffffff00u) | (unsigned)(255 - pos); }
; DI void phase10(const Params& P, char* smem) {
;     ...
;     C2[0] = candkey(v1[3] + v2[3], 51);
;     C2[1] = candkey(v1[4] + v2[0], 64);
;     C2[2] = candkey(v1[4] + v2[1], 65);
;     C2[3] = candkey(v1[4] + v2[2], 66);
;     C2[4] = candkey(v1[5] + v2[0], 80);
;     C2[5] = candkey(v1[5] + v2[1], 81);
;     C2[6] = candkey(v1[6] + v2[0], 96);
;     C2[7] = candkey(v1[6] + v2[1], 97);
;     C2[8] = candkey(v1[7] + v2[0], 112);
;     C2[9] = candkey(v1[7] + v2[1], 113);
;     C2[10] = candkey(v1[8] + v2[0], 128);
;     C2[11] = candkey(v1[9] + v2[0], 144);
;     C2[12] = candkey(v1[10] + v2[0], 160);
;     C2[13] = candkey(v1[11] + v2[0], 176);
;     C2[14] = candkey(v1[12] + v2[0], 192);
;     C2[15] = candkey(v1[13] + v2[0], 208);
;     C3[0] = candkey(v1[14] + v2[0], 224);
;     C3[1] = candkey(v1[15] + v2[0], 240);
;     C3[2] = 0u;
;     C3[3] = 0u;
;     C3[4] = 0u;
;     C3[5] = 0u;
;     C3[6] = 0u;
;     C3[7] = 0u;
;     C3[8] = 0u;
;     C3[9] = 0u;
;     C3[10] = 0u;
;     C3[11] = 0u;
;     C3[12] = 0u;
;     C3[13] = 0u;
;     C3[14] = 0u;
;     C3[15] = 0u;
;     SORT16(C1) SORT16(C2) SORT16(C3)
	v_pk_add_f32 v[8:9], v[6:7], v[10:11] op_sel_hi:[0,1]
	v_cmp_lt_i32_e32 vcc, -1, v9
	v_and_b32_e32 v9, 0xffffff00, v9
	v_xor_b32_sdwa v11, v31, v27 dst_sel:DWORD dst_unused:UNUSED_PAD src0_sel:WORD_1 src1_sel:DWORD
	v_cndmask_b32_e32 v7, v28, v29, vcc
	v_bitop3_b32 v7, v7, s0, v9 bitop3:0xde
	v_and_b32_sdwa v9, v31, s57 dst_sel:DWORD dst_unused:UNUSED_PAD src0_sel:WORD_1 src1_sel:DWORD
	v_cmp_gt_i32_e32 vcc, 0, v31
	v_and_b32_sdwa v10, v30, s57 dst_sel:DWORD dst_unused:UNUSED_PAD src0_sel:WORD_1 src1_sel:DWORD
	v_pk_add_f32 v[4:5], v[4:5], v[6:7] op_sel_hi:[1,0]
	v_cndmask_b32_e32 v9, v11, v9, vcc
	v_cmp_gt_i32_e32 vcc, 0, v30
	v_cvt_f32_f16_e32 v11, v9
	v_max_u32_e32 v21, v14, v79
	v_cndmask_b32_e32 v10, v33, v10, vcc
	v_cvt_f32_f16_e32 v10, v10
	v_cmp_lt_i32_e32 vcc, -1, v8
	v_and_b32_e32 v8, 0xffffff00, v8
	v_xor_b32_sdwa v33, v1, v27 dst_sel:DWORD dst_unused:UNUSED_PAD src0_sel:WORD_1 src1_sel:DWORD
	v_cndmask_b32_e32 v9, v28, v29, vcc
	v_bitop3_b32 v30, v9, s88, v8 bitop3:0xde
	v_pk_add_f32 v[8:9], v[6:7], v[10:11] op_sel_hi:[0,1]
	v_cmp_lt_i32_e32 vcc, -1, v9
	v_and_b32_e32 v9, 0xffffff00, v9
	v_xor_b32_sdwa v11, v3, v27 dst_sel:DWORD dst_unused:UNUSED_PAD src0_sel:WORD_1 src1_sel:DWORD
	v_cndmask_b32_e32 v10, v28, v29, vcc
	v_bitop3_b32 v31, v10, s89, v9 bitop3:0xde
	v_and_b32_sdwa v9, v3, s57 dst_sel:DWORD dst_unused:UNUSED_PAD src0_sel:WORD_1 src1_sel:DWORD
	v_cmp_gt_i32_e32 vcc, 0, v3
	v_and_b32_sdwa v10, v1, s57 dst_sel:DWORD dst_unused:UNUSED_PAD src0_sel:WORD_1 src1_sel:DWORD
	v_min_u32_e32 v14, v14, v79
	v_cndmask_b32_e32 v3, v11, v9, vcc
	v_cmp_gt_i32_e32 vcc, 0, v1
	v_cvt_f32_f16_e32 v11, v3
	v_and_b32_e32 v3, 0xffffff00, v8
	v_cndmask_b32_e32 v1, v33, v10, vcc
	v_cvt_f32_f16_e32 v10, v1
	v_cmp_lt_i32_e32 vcc, -1, v8
	v_max_u32_e32 v33, v67, v66
	v_min_u32_e32 v66, v67, v66
	v_pk_add_f32 v[8:9], v[6:7], v[10:11] op_sel_hi:[0,1]
	v_cndmask_b32_e32 v1, v28, v29, vcc
	v_cmp_lt_i32_e32 vcc, -1, v9
	v_bitop3_b32 v1, v1, s90, v3 bitop3:0xde
	v_and_b32_e32 v9, 0xffffff00, v9
	v_cndmask_b32_e32 v3, v28, v29, vcc
	v_cmp_lt_i32_e32 vcc, -1, v8
	v_bitop3_b32 v3, v3, 63, v9 bitop3:0xde
	v_and_b32_e32 v8, 0xffffff00, v8
	v_cndmask_b32_e32 v9, v28, v29, vcc
	v_cmp_lt_i32_e32 vcc, -1, v5
	v_and_b32_e32 v5, 0xffffff00, v5
	v_bitop3_b32 v8, v9, 47, v8 bitop3:0xde
	v_cndmask_b32_e32 v6, v28, v29, vcc
	v_cmp_lt_i32_e32 vcc, -1, v4
	v_bitop3_b32 v5, v6, 31, v5 bitop3:0xde
	v_and_b32_e32 v4, 0xffffff00, v4
	v_cndmask_b32_e32 v6, v28, v29, vcc
	v_bitop3_b32 v4, v6, 15, v4 bitop3:0xde
	v_max_u32_e32 v6, v69, v70
	v_min_u32_e32 v9, v69, v70
	v_max_u32_e32 v10, v71, v72
	v_min_u32_e32 v11, v71, v72
	v_max_u32_e32 v67, v64, v73
	v_min_u32_e32 v64, v64, v73
	v_max_u32_e32 v69, v74, v75
	v_min_u32_e32 v70, v74, v75
	v_max_u32_e32 v71, v76, v77
	v_min_u32_e32 v72, v76, v77
	v_max_u32_e32 v73, v22, v78
	v_min_u32_e32 v22, v22, v78
	v_max_u32_e32 v74, v25, v24
	v_min_u32_e32 v24, v25, v24
	v_max_u32_e32 v25, v6, v10
	v_min_u32_e32 v6, v6, v10
	v_max_u32_e32 v10, v9, v11
	v_min_u32_e32 v9, v9, v11
	v_max_u32_e32 v11, v33, v67
	v_min_u32_e32 v33, v33, v67
	v_max_u32_e32 v67, v66, v64
	v_min_u32_e32 v64, v66, v64
	v_max_u32_e32 v66, v69, v71
	v_min_u32_e32 v69, v69, v71
	v_max_u32_e32 v71, v70, v72
	v_min_u32_e32 v70, v70, v72
	v_max_u32_e32 v72, v73, v74
	v_min_u32_e32 v73, v73, v74
	v_max_u32_e32 v74, v22, v24
	v_min_u32_e32 v22, v22, v24
	v_max_u32_e32 v24, v10, v6
	v_min_u32_e32 v6, v10, v6
	v_max_u32_e32 v10, v67, v33
	v_min_u32_e32 v33, v67, v33
	v_max_u32_e32 v67, v71, v69
	v_min_u32_e32 v69, v71, v69
	v_max_u32_e32 v71, v74, v73
	v_min_u32_e32 v73, v74, v73
	v_max_u32_e32 v74, v25, v11
	v_min_u32_e32 v11, v25, v11
	v_max_u32_e32 v25, v24, v10
	v_min_u32_e32 v10, v24, v10
	v_max_u32_e32 v24, v6, v33
	v_min_u32_e32 v6, v6, v33
	v_max_u32_e32 v33, v9, v64
	v_min_u32_e32 v9, v9, v64
	v_max_u32_e32 v64, v66, v72
	v_min_u32_e32 v66, v66, v72
	v_max_u32_e32 v72, v67, v71
	v_min_u32_e32 v67, v67, v71
	v_max_u32_e32 v71, v69, v73
	v_min_u32_e32 v69, v69, v73
	v_max_u32_e32 v73, v70, v22
	v_min_u32_e32 v22, v70, v22
	v_max_u32_e32 v70, v24, v11
	v_min_u32_e32 v11, v24, v11
	v_max_u32_e32 v24, v33, v10
	v_min_u32_e32 v10, v33, v10
	v_max_u32_e32 v33, v71, v66
	v_min_u32_e32 v66, v71, v66
	v_max_u32_e32 v71, v73, v67
	v_min_u32_e32 v67, v73, v67
	v_max_u32_e32 v73, v25, v70
	v_min_u32_e32 v25, v25, v70
	v_max_u32_e32 v70, v24, v11
	v_min_u32_e32 v11, v24, v11
	v_max_u32_e32 v24, v10, v6
	v_min_u32_e32 v6, v10, v6
	v_max_u32_e32 v10, v72, v33
	v_min_u32_e32 v33, v72, v33
	v_max_u32_e32 v72, v71, v66
	v_min_u32_e32 v66, v71, v66
	v_max_u32_e32 v71, v67, v69
	v_min_u32_e32 v67, v67, v69
	v_max_u32_e32 v79, v16, v80
	v_min_u32_e32 v16, v16, v80
	v_max_u32_e32 v80, v18, v32
	v_min_u32_e32 v18, v18, v32
	v_max_u32_e32 v32, v7, v30
	v_min_u32_e32 v7, v7, v30
	v_max_u32_e32 v30, v31, v1
	v_min_u32_e32 v1, v31, v1
	v_max_u32_e32 v31, v3, v8
	v_min_u32_e32 v3, v3, v8
	v_min_u32_e32 v69, v74, v64
	v_max_u32_e32 v75, v73, v10
	v_min_u32_e32 v10, v73, v10
	v_max_u32_e32 v73, v25, v33
	v_min_u32_e32 v25, v25, v33
	v_max_u32_e32 v33, v70, v72
	v_min_u32_e32 v70, v70, v72
	v_max_u32_e32 v72, v11, v66
	v_min_u32_e32 v11, v11, v66
	v_max_u32_e32 v66, v24, v71
	v_min_u32_e32 v24, v24, v71
	v_max_u32_e32 v71, v6, v67
	v_min_u32_e32 v6, v6, v67
	v_max_u32_e32 v67, v9, v22
	v_max_u32_e32 v8, v84, v13
	v_min_u32_e32 v13, v84, v13
	v_max_u32_e32 v84, v12, v20
	v_min_u32_e32 v12, v12, v20
	v_max_u32_e32 v20, v21, v79
	v_min_u32_e32 v21, v21, v79
	v_max_u32_e32 v79, v14, v16
	v_min_u32_e32 v14, v14, v16
	v_max_u32_e32 v16, v80, v32
	v_min_u32_e32 v32, v80, v32
	v_max_u32_e32 v80, v18, v7
; DI void phase10(const Params& P, char* smem) {
;     ...
;     SORT16(C1) SORT16(C2) SORT16(C3)
;     MERGE16(C0, C1) MERGE16(C0, C2) MERGE16(C0, C3)
	v_min_u32_e32 v7, v18, v7
	v_max_u32_e32 v18, v30, v31
	v_min_u32_e32 v30, v30, v31
	v_max_u32_e32 v31, v1, v3
	v_min_u32_e32 v9, v9, v22
	v_max_u32_e32 v22, v72, v69
	v_min_u32_e32 v69, v72, v69
	v_max_u32_e32 v72, v66, v10
	v_min_u32_e32 v10, v66, v10
	v_max_u32_e32 v66, v71, v25
	v_min_u32_e32 v25, v71, v25
	v_max_u32_e32 v71, v67, v70
	v_min_u32_e32 v67, v67, v70
	v_min_u32_e32 v1, v1, v3
	v_max_u32_e32 v3, v84, v13
	v_min_u32_e32 v13, v84, v13
	v_max_u32_e32 v84, v79, v21
	v_min_u32_e32 v21, v79, v21
	v_max_u32_e32 v79, v80, v32
	v_min_u32_e32 v32, v80, v32
	v_max_u32_e32 v80, v31, v30
	v_min_u32_e32 v30, v31, v30
	v_max_u32_e32 v70, v73, v22
	v_min_u32_e32 v22, v73, v22
	v_max_u32_e32 v73, v33, v72
	v_min_u32_e32 v33, v33, v72
	v_max_u32_e32 v72, v66, v69
	v_min_u32_e32 v66, v66, v69
	v_max_u32_e32 v69, v71, v10
	v_min_u32_e32 v10, v71, v10
	v_max_u32_e32 v71, v25, v11
	v_min_u32_e32 v11, v25, v11
	v_max_u32_e32 v25, v67, v24
	v_min_u32_e32 v24, v67, v24
	v_max_u32_e32 v31, v8, v20
	v_min_u32_e32 v8, v8, v20
	v_max_u32_e32 v20, v3, v84
	v_min_u32_e32 v3, v3, v84
	v_max_u32_e32 v84, v13, v21
	v_min_u32_e32 v13, v13, v21
	v_max_u32_e32 v21, v12, v14
	v_min_u32_e32 v12, v12, v14
	v_max_u32_e32 v14, v16, v18
	v_min_u32_e32 v16, v16, v18
	v_max_u32_e32 v18, v79, v80
	v_min_u32_e32 v79, v79, v80
	v_max_u32_e32 v80, v32, v30
	v_min_u32_e32 v30, v32, v30
	v_max_u32_e32 v32, v7, v1
	v_min_u32_e32 v67, v75, v70
	v_min_u32_e32 v76, v73, v22
	v_min_u32_e32 v77, v33, v72
	v_min_u32_e32 v78, v69, v66
	v_min_u32_e32 v81, v10, v71
	v_min_u32_e32 v82, v25, v11
	v_min_u32_e32 v83, v24, v6
	v_min_u32_e32 v1, v7, v1
	v_max_u32_e32 v7, v84, v8
	v_min_u32_e32 v8, v84, v8
	v_max_u32_e32 v84, v21, v3
	v_min_u32_e32 v3, v21, v3
	v_max_u32_e32 v21, v80, v16
	v_min_u32_e32 v16, v80, v16
	v_max_u32_e32 v80, v32, v79
	v_min_u32_e32 v32, v32, v79
	v_max_u32_e32 v79, v20, v7
	v_min_u32_e32 v7, v20, v7
	v_max_u32_e32 v20, v84, v8
	v_min_u32_e32 v8, v84, v8
	v_max_u32_e32 v84, v3, v13
	v_min_u32_e32 v3, v3, v13
	v_max_u32_e32 v13, v18, v21
	v_min_u32_e32 v18, v18, v21
	v_max_u32_e32 v21, v80, v16
	v_min_u32_e32 v16, v80, v16
	v_max_u32_e32 v80, v32, v30
	v_min_u32_e32 v30, v32, v30
	v_max_u32_e32 v9, v35, v9
	v_max_u32_e32 v35, v36, v83
	v_max3_u32 v6, v37, v24, v6
	v_max_u32_e32 v24, v38, v82
	v_max3_u32 v11, v39, v25, v11
	v_max_u32_e32 v25, v40, v81
	v_max3_u32 v10, v41, v10, v71
	v_max_u32_e32 v36, v57, v78
	v_max3_u32 v37, v58, v69, v66
	v_max_u32_e32 v38, v59, v77
	v_max3_u32 v33, v60, v33, v72
	v_max_u32_e32 v39, v61, v76
	v_max3_u32 v22, v62, v73, v22
	v_max_u32_e32 v40, v63, v67
	v_max3_u32 v41, v65, v75, v70
	v_max3_u32 v57, v68, v74, v64
	v_min_u32_e32 v32, v31, v14
	v_max_u32_e32 v85, v79, v13
	v_min_u32_e32 v13, v79, v13
	v_max_u32_e32 v79, v7, v18
	v_min_u32_e32 v7, v7, v18
	v_max_u32_e32 v18, v20, v21
	v_min_u32_e32 v20, v20, v21
	v_max_u32_e32 v21, v8, v16
	v_min_u32_e32 v8, v8, v16
	v_max_u32_e32 v16, v84, v80
	v_min_u32_e32 v80, v84, v80
	v_max_u32_e32 v84, v3, v30
	v_min_u32_e32 v3, v3, v30
	v_max_u32_e32 v30, v12, v1
	v_max_u32_e32 v58, v9, v37
	v_min_u32_e32 v9, v9, v37
	v_max_u32_e32 v37, v35, v38
	v_min_u32_e32 v35, v35, v38
	v_max_u32_e32 v38, v6, v33
	v_min_u32_e32 v6, v6, v33
	v_max_u32_e32 v33, v24, v39
	v_min_u32_e32 v24, v24, v39
	v_max_u32_e32 v39, v11, v22
	v_min_u32_e32 v11, v11, v22
	v_max_u32_e32 v22, v25, v40
	v_min_u32_e32 v25, v25, v40
	v_max_u32_e32 v40, v10, v41
	v_min_u32_e32 v10, v10, v41
	v_max_u32_e32 v41, v36, v57
	v_min_u32_e32 v36, v36, v57
	v_min_u32_e32 v1, v12, v1
	v_max_u32_e32 v12, v21, v32
	v_min_u32_e32 v21, v21, v32
	v_max_u32_e32 v32, v16, v13
	v_min_u32_e32 v13, v16, v13
	v_max_u32_e32 v16, v84, v7
	v_min_u32_e32 v7, v84, v7
	v_max_u32_e32 v84, v30, v20
	v_min_u32_e32 v20, v30, v20
	v_max_u32_e32 v57, v58, v39
	v_min_u32_e32 v39, v58, v39
	v_max_u32_e32 v58, v37, v22
	v_min_u32_e32 v22, v37, v22
	v_max_u32_e32 v37, v38, v40
	v_min_u32_e32 v38, v38, v40
	v_max_u32_e32 v40, v33, v41
	v_min_u32_e32 v33, v33, v41
	v_max_u32_e32 v41, v9, v11
	v_min_u32_e32 v9, v9, v11
	v_max_u32_e32 v11, v35, v25
	v_min_u32_e32 v25, v35, v25
	v_max_u32_e32 v35, v6, v10
	v_min_u32_e32 v6, v6, v10
	v_max_u32_e32 v10, v24, v36
	v_min_u32_e32 v24, v24, v36
	v_max_u32_e32 v30, v79, v12
	v_min_u32_e32 v12, v79, v12
	v_max_u32_e32 v79, v18, v32
	v_min_u32_e32 v18, v18, v32
	v_max_u32_e32 v32, v16, v21
	v_min_u32_e32 v16, v16, v21
	v_max_u32_e32 v21, v84, v13
; DI unsigned lut4(const unsigned (&W)[4], int a) { const int j = a >> 2; const unsigned w = j == 0 ? W[0] : (j == 1 ? W[1] : (j == 2 ? W[2] : W[3])); return (w >> ((a & 3) * 8)) & 0xffu; }
; DI void phase10(const Params& P, char* smem) {
;     ...
;     MERGE16(C0, C1) MERGE16(C0, C2) MERGE16(C0, C3)
;     float e[16]; int te[16]; float sum = 0.f;
;     const float tv0 = [&]() { const unsigned o = C0[0] & 0xffffff00u; return __uint_as_float((o >> 31) ? (o ^ 0x80000000u) : ~o); }();
; #pragma unroll
;     for (int k = 0; k < 16; ++k) {
;       const unsigned key = C0[k]; const unsigned o = key & 0xffffff00u;
;       const float val = __uint_as_float((o >> 31) ? (o ^ 0x80000000u) : ~o);
;       const int pos = 255 - (int)(key & 255u);
;       te[k] = (int)(lut4(W1, pos >> 4) * 128u + lut4(W2, pos & 15));
;       e[k] = __expf(val - tv0); sum += e[k];
	v_min_u32_e32 v13, v84, v13
	v_max_u32_e32 v84, v7, v8
	v_min_u32_e32 v7, v7, v8
	v_max_u32_e32 v8, v20, v80
	v_min_u32_e32 v20, v20, v80
	v_max_u32_e32 v36, v57, v37
	v_min_u32_e32 v37, v57, v37
	v_max_u32_e32 v57, v58, v40
	v_min_u32_e32 v40, v58, v40
	v_max_u32_e32 v58, v39, v38
	v_min_u32_e32 v38, v39, v38
	v_max_u32_e32 v39, v22, v33
	v_min_u32_e32 v22, v22, v33
	v_max_u32_e32 v33, v41, v35
	v_min_u32_e32 v35, v41, v35
	v_max_u32_e32 v41, v11, v10
	v_min_u32_e32 v10, v11, v10
	v_max_u32_e32 v11, v9, v6
	v_min_u32_e32 v6, v9, v6
	v_max_u32_e32 v9, v25, v24
	v_min_u32_e32 v24, v25, v24
	v_max_u32_e32 v80, v85, v30
	v_min_u32_e32 v30, v85, v30
	v_max_u32_e32 v85, v79, v12
	v_min_u32_e32 v12, v79, v12
	v_max_u32_e32 v79, v18, v32
	v_min_u32_e32 v18, v18, v32
	v_max_u32_e32 v32, v21, v16
	v_min_u32_e32 v16, v21, v16
	v_max_u32_e32 v21, v13, v84
	v_min_u32_e32 v13, v13, v84
	v_max_u32_e32 v84, v8, v7
	v_min_u32_e32 v7, v8, v7
	v_max_u32_e32 v8, v20, v3
	v_min_u32_e32 v3, v20, v3
	v_min_u32_e32 v25, v36, v57
	v_min_u32_e32 v59, v37, v40
	v_min_u32_e32 v60, v58, v39
	v_min_u32_e32 v61, v38, v22
	v_min_u32_e32 v62, v33, v41
	v_min_u32_e32 v63, v35, v10
	v_min_u32_e32 v64, v11, v9
	v_min_u32_e32 v65, v6, v24
	v_max3_u32 v1, v36, v57, v1
	v_max_u32_e32 v3, v25, v3
	v_max3_u32 v8, v37, v40, v8
	v_max_u32_e32 v7, v59, v7
	v_max3_u32 v25, v58, v39, v84
	v_max_u32_e32 v13, v60, v13
	v_max3_u32 v21, v38, v22, v21
	v_max_u32_e32 v16, v61, v16
	v_max3_u32 v22, v33, v41, v32
	v_max_u32_e32 v18, v62, v18
	v_max3_u32 v10, v35, v10, v79
	v_max_u32_e32 v12, v63, v12
	v_max3_u32 v9, v11, v9, v85
	v_max_u32_e32 v11, v64, v30
	v_max3_u32 v6, v6, v24, v80
	v_max3_u32 v14, v65, v31, v14
	v_max_u32_e32 v24, v1, v22
	v_min_u32_e32 v1, v1, v22
	v_max_u32_e32 v22, v3, v18
	v_min_u32_e32 v3, v3, v18
	v_max_u32_e32 v18, v8, v10
	v_min_u32_e32 v8, v8, v10
	v_max_u32_e32 v10, v7, v12
	v_min_u32_e32 v7, v7, v12
	v_max_u32_e32 v12, v25, v9
	v_min_u32_e32 v9, v25, v9
	v_max_u32_e32 v25, v13, v11
	v_min_u32_e32 v11, v13, v11
	v_max_u32_e32 v13, v21, v6
	v_min_u32_e32 v6, v21, v6
	v_max_u32_e32 v21, v16, v14
	v_min_u32_e32 v14, v16, v14
	v_max_u32_e32 v16, v24, v12
	v_min_u32_e32 v12, v24, v12
	v_max_u32_e32 v24, v22, v25
	v_min_u32_e32 v22, v22, v25
	v_max_u32_e32 v25, v18, v13
	v_min_u32_e32 v13, v18, v13
	v_max_u32_e32 v18, v10, v21
	v_min_u32_e32 v10, v10, v21
	v_max_u32_e32 v21, v1, v9
	v_min_u32_e32 v1, v1, v9
	v_max_u32_e32 v9, v3, v11
	v_min_u32_e32 v3, v3, v11
	v_max_u32_e32 v11, v8, v6
	v_min_u32_e32 v6, v8, v6
	v_max_u32_e32 v8, v7, v14
	v_min_u32_e32 v7, v7, v14
	v_max_u32_e32 v14, v16, v25
	v_min_u32_e32 v16, v16, v25
	v_max_u32_e32 v25, v24, v18
	v_min_u32_e32 v18, v24, v18
	v_max_u32_e32 v24, v12, v13
	v_min_u32_e32 v12, v12, v13
	v_max_u32_e32 v13, v22, v10
	v_min_u32_e32 v10, v22, v10
	v_max_u32_e32 v22, v21, v11
	v_min_u32_e32 v11, v21, v11
	v_max_u32_e32 v21, v9, v8
	v_min_u32_e32 v8, v9, v8
	v_max_u32_e32 v9, v1, v6
	v_min_u32_e32 v1, v1, v6
	v_max_u32_e32 v6, v3, v7
	v_min_u32_e32 v3, v3, v7
	v_min_u32_e32 v20, v5, v4
	v_max_u32_e32 v69, v9, v6
	v_min_u32_e32 v70, v9, v6
	v_min_u32_e32 v6, v1, v3
	v_max_u32_e32 v57, v14, v25
	v_min_u32_e32 v58, v14, v25
	v_max_u32_e32 v59, v16, v18
	v_min_u32_e32 v60, v16, v18
	v_max_u32_e32 v61, v24, v13
	v_min_u32_e32 v62, v24, v13
	v_max_u32_e32 v63, v12, v10
	v_min_u32_e32 v64, v12, v10
	v_max_u32_e32 v65, v22, v21
	v_min_u32_e32 v66, v22, v21
	v_max_u32_e32 v67, v11, v8
	v_min_u32_e32 v68, v11, v8
	v_max3_u32 v71, v1, v3, v20
	v_max3_u32 v72, v6, v5, v4
	v_max_u32_e32 v11, v57, v65
	v_max_u32_e32 v12, v58, v66
	v_max_u32_e32 v13, v59, v67
	v_max_u32_e32 v32, v60, v68
	v_max_u32_e32 v33, v61, v69
	v_max_u32_e32 v35, v62, v70
	v_max_u32_e32 v36, v63, v71
	v_max_u32_e32 v37, v64, v72
	v_max_u32_e32 v9, v11, v33
	v_max_u32_e32 v10, v12, v35
	v_max_u32_e32 v22, v13, v36
	v_max_u32_e32 v24, v32, v37
	v_max_u32_e32 v8, v9, v22
	v_max_u32_e32 v18, v10, v24
	v_max_u32_e32 v4, v8, v18
	v_bitop3_b32 v1, v4, s3, v4 bitop3:0xc
	v_cmp_lt_u32_e32 vcc, 63, v1
	v_mov_b32_e32 v3, v15
	s_and_saveexec_b64 s[0:1], vcc
	s_cbranch_execz .LBB0_1193
	v_lshrrev_b32_e32 v5, 6, v1
	v_cmp_lt_i32_e32 vcc, 1, v5
	s_mov_b64 s[6:7], 0
	s_and_saveexec_b64 s[8:9], vcc
	s_xor_b64 s[8:9], exec, s[8:9]
	s_cbranch_execnz .LBB0_1381
	s_or_saveexec_b64 s[8:9], s[8:9]
	v_mov_b32_e32 v3, v19
	s_xor_b64 exec, exec, s[8:9]
	s_cbranch_execnz .LBB0_1384
